# GEMM K-loops: MFMA issue order inside each 16-MFMA segment changed to a snake (same-accumulator k-pairs adjacent, k order alternating, consecutive MFMAs share C, A or B operand) to cut operand togglin
# speedup vs baseline: 1.0096x; 1.0096x over previous
.LBB0_95:
	s_add_u32 s16, s14, 0xfff80080
	s_addc_u32 s17, s15, -1
	s_add_i32 s42, 0, 0x10000
	v_add_u32_e32 v145, s42, v142
	ds_read_b128 v[146:149], v145
	ds_read_b128 v[150:153], v145 offset:1024
	ds_read_b128 v[154:157], v145 offset:2048
	ds_read_b128 v[158:161], v145 offset:3072
	s_cmp_eq_u32 s41, 28
	s_cselect_b32 s19, s9, s17
	s_cselect_b32 s18, s37, s16
	s_cselect_b32 s17, s7, s40
	s_cselect_b32 s16, s38, s39
	s_add_i32 m0, s27, 0xc000
	ds_read_b128 v[162:165], v144
	ds_read_b128 v[166:169], v144 offset:1024
	ds_read_b128 v[170:173], v144 offset:2048
	ds_read_b128 v[174:177], v144 offset:3072
	ds_read_b128 v[178:181], v144 offset:4096
	ds_read_b128 v[182:185], v144 offset:5120
	ds_read_b128 v[186:189], v144 offset:6144
	ds_read_b128 v[190:193], v144 offset:7168
	global_load_lds_dwordx4 v138, s[14:15]
	s_add_i32 m0, s27, 0xe000
	s_nop 0
	global_load_lds_dwordx4 v140, s[14:15]
	s_waitcnt lgkmcnt(8)
	s_barrier
	s_waitcnt lgkmcnt(0)
	s_setprio 1
	s_waitcnt lgkmcnt(0)
	v_mfma_f32_16x16x32_bf16 v[128:131], v[146:149], v[162:165], v[128:131]
	v_mfma_f32_16x16x32_bf16 v[128:131], v[150:153], v[166:169], v[128:131]
	v_mfma_f32_16x16x32_bf16 v[120:123], v[150:153], v[174:177], v[120:123]
	v_mfma_f32_16x16x32_bf16 v[120:123], v[146:149], v[170:173], v[120:123]
	v_mfma_f32_16x16x32_bf16 v[104:107], v[146:149], v[178:181], v[104:107]
	v_mfma_f32_16x16x32_bf16 v[104:107], v[150:153], v[182:185], v[104:107]
	v_mfma_f32_16x16x32_bf16 v[88:91], v[150:153], v[190:193], v[88:91]
	v_mfma_f32_16x16x32_bf16 v[88:91], v[146:149], v[186:189], v[88:91]
	v_mfma_f32_16x16x32_bf16 v[84:87], v[154:157], v[186:189], v[84:87]
	v_mfma_f32_16x16x32_bf16 v[84:87], v[158:161], v[190:193], v[84:87]
	v_mfma_f32_16x16x32_bf16 v[100:103], v[158:161], v[182:185], v[100:103]
	v_mfma_f32_16x16x32_bf16 v[100:103], v[154:157], v[178:181], v[100:103]
	v_mfma_f32_16x16x32_bf16 v[116:119], v[154:157], v[170:173], v[116:119]
	v_mfma_f32_16x16x32_bf16 v[116:119], v[158:161], v[174:177], v[116:119]
	v_mfma_f32_16x16x32_bf16 v[124:127], v[158:161], v[166:169], v[124:127]
	s_barrier
	v_mfma_f32_16x16x32_bf16 v[124:127], v[154:157], v[162:165], v[124:127]
	s_setprio 0
	s_add_i32 s44, 0, 0x14000
	s_add_i32 s42, s42, s26
	v_add_u32_e32 v145, s44, v142
	v_lshl_add_u64 v[212:213], s[16:17], 0, v[2:3]
	s_mov_b32 m0, s42
	ds_read_b128 v[194:197], v145
	ds_read_b128 v[200:203], v145 offset:1024
	ds_read_b128 v[204:207], v145 offset:2048
	ds_read_b128 v[208:211], v145 offset:3072
	global_load_lds_dwordx4 v[212:213], off
	v_lshl_add_u64 v[214:215], s[16:17], 0, v[132:133]
	s_add_i32 m0, s42, 0x2000
	s_nop 0
	global_load_lds_dwordx4 v[214:215], off
	s_barrier
	s_waitcnt lgkmcnt(0)
	s_setprio 1
	s_waitcnt lgkmcnt(0)
	v_mfma_f32_16x16x32_bf16 v[112:115], v[194:197], v[162:165], v[112:115]
	v_mfma_f32_16x16x32_bf16 v[112:115], v[200:203], v[166:169], v[112:115]
	v_mfma_f32_16x16x32_bf16 v[96:99], v[200:203], v[174:177], v[96:99]
	v_mfma_f32_16x16x32_bf16 v[96:99], v[194:197], v[170:173], v[96:99]
	v_mfma_f32_16x16x32_bf16 v[80:83], v[194:197], v[178:181], v[80:83]
	v_mfma_f32_16x16x32_bf16 v[80:83], v[200:203], v[182:185], v[80:83]
	v_mfma_f32_16x16x32_bf16 v[72:75], v[200:203], v[190:193], v[72:75]
	v_mfma_f32_16x16x32_bf16 v[72:75], v[194:197], v[186:189], v[72:75]
	v_mfma_f32_16x16x32_bf16 v[68:71], v[204:207], v[186:189], v[68:71]
	v_mfma_f32_16x16x32_bf16 v[68:71], v[208:211], v[190:193], v[68:71]
	v_mfma_f32_16x16x32_bf16 v[76:79], v[208:211], v[182:185], v[76:79]
	v_mfma_f32_16x16x32_bf16 v[76:79], v[204:207], v[178:181], v[76:79]
	v_mfma_f32_16x16x32_bf16 v[92:95], v[204:207], v[170:173], v[92:95]
	v_mfma_f32_16x16x32_bf16 v[92:95], v[208:211], v[174:177], v[92:95]
	v_mfma_f32_16x16x32_bf16 v[108:111], v[208:211], v[166:169], v[108:111]
	s_barrier
	v_mfma_f32_16x16x32_bf16 v[108:111], v[204:207], v[162:165], v[108:111]
	s_setprio 0
	s_mov_b32 m0, s27
	v_lshl_add_u64 v[216:217], s[18:19], 0, v[136:137]
	ds_read_b128 v[162:165], v144 offset:16384
	ds_read_b128 v[166:169], v144 offset:17408
	ds_read_b128 v[170:173], v144 offset:18432
	ds_read_b128 v[174:177], v144 offset:19456
	ds_read_b128 v[178:181], v144 offset:20480
	ds_read_b128 v[182:185], v144 offset:21504
	ds_read_b128 v[186:189], v144 offset:22528
	ds_read_b128 v[190:193], v144 offset:23552
	global_load_lds_dwordx4 v[216:217], off
	v_lshl_add_u64 v[218:219], s[18:19], 0, v[134:135]
	s_mov_b32 m0, s28
	s_nop 0
	global_load_lds_dwordx4 v[218:219], off
	s_waitcnt vmcnt(10)
	s_barrier
	s_waitcnt lgkmcnt(0)
	s_setprio 1
	s_waitcnt lgkmcnt(0)
	v_mfma_f32_16x16x32_bf16 v[64:67], v[146:149], v[162:165], v[64:67]
	v_mfma_f32_16x16x32_bf16 v[64:67], v[150:153], v[166:169], v[64:67]
	v_mfma_f32_16x16x32_bf16 v[56:59], v[150:153], v[174:177], v[56:59]
	v_mfma_f32_16x16x32_bf16 v[56:59], v[146:149], v[170:173], v[56:59]
	v_mfma_f32_16x16x32_bf16 v[40:43], v[146:149], v[178:181], v[40:43]
	v_mfma_f32_16x16x32_bf16 v[40:43], v[150:153], v[182:185], v[40:43]
	v_mfma_f32_16x16x32_bf16 v[24:27], v[150:153], v[190:193], v[24:27]
	v_mfma_f32_16x16x32_bf16 v[24:27], v[146:149], v[186:189], v[24:27]
	v_mfma_f32_16x16x32_bf16 v[20:23], v[154:157], v[186:189], v[20:23]
	v_mfma_f32_16x16x32_bf16 v[20:23], v[158:161], v[190:193], v[20:23]
	v_mfma_f32_16x16x32_bf16 v[36:39], v[158:161], v[182:185], v[36:39]
	v_mfma_f32_16x16x32_bf16 v[36:39], v[154:157], v[178:181], v[36:39]
	v_mfma_f32_16x16x32_bf16 v[52:55], v[154:157], v[170:173], v[52:55]
	v_mfma_f32_16x16x32_bf16 v[52:55], v[158:161], v[174:177], v[52:55]
	v_mfma_f32_16x16x32_bf16 v[60:63], v[158:161], v[166:169], v[60:63]
	s_barrier
	v_mfma_f32_16x16x32_bf16 v[60:63], v[154:157], v[162:165], v[60:63]
	s_setprio 0
	s_add_u32 s42, s16, 0x20000
	s_addc_u32 s43, s17, 0
	s_add_i32 s44, s44, s26
	s_mov_b32 m0, s44
	s_nop 0
	global_load_lds_dwordx4 v2, s[42:43]
	s_add_i32 m0, s44, 0x2000
	s_nop 0
	global_load_lds_dwordx4 v132, s[42:43]
	s_add_i32 s42, 0, 0x18000
	v_add_u32_e32 v145, s42, v142
	ds_read_b128 v[146:149], v145
	ds_read_b128 v[150:153], v145 offset:1024
	ds_read_b128 v[154:157], v145 offset:2048
	ds_read_b128 v[158:161], v145 offset:3072
	s_waitcnt vmcnt(6)
	s_barrier
	s_setprio 1
	v_mfma_f32_16x16x32_bf16 v[48:51], v[194:197], v[162:165], v[48:51]
	v_mfma_f32_16x16x32_bf16 v[48:51], v[200:203], v[166:169], v[48:51]
	v_mfma_f32_16x16x32_bf16 v[32:35], v[200:203], v[174:177], v[32:35]
	v_mfma_f32_16x16x32_bf16 v[32:35], v[194:197], v[170:173], v[32:35]
	v_mfma_f32_16x16x32_bf16 v[16:19], v[194:197], v[178:181], v[16:19]
	v_mfma_f32_16x16x32_bf16 v[16:19], v[200:203], v[182:185], v[16:19]
	v_mfma_f32_16x16x32_bf16 v[8:11], v[200:203], v[190:193], v[8:11]
	v_mfma_f32_16x16x32_bf16 v[8:11], v[194:197], v[186:189], v[8:11]
	v_mfma_f32_16x16x32_bf16 v[4:7], v[204:207], v[186:189], v[4:7]
	v_mfma_f32_16x16x32_bf16 v[4:7], v[208:211], v[190:193], v[4:7]
	v_mfma_f32_16x16x32_bf16 v[12:15], v[208:211], v[182:185], v[12:15]
	v_mfma_f32_16x16x32_bf16 v[12:15], v[204:207], v[178:181], v[12:15]
	v_mfma_f32_16x16x32_bf16 v[28:31], v[204:207], v[170:173], v[28:31]
	v_mfma_f32_16x16x32_bf16 v[28:31], v[208:211], v[174:177], v[28:31]
	v_mfma_f32_16x16x32_bf16 v[44:47], v[208:211], v[166:169], v[44:47]
	s_barrier
	v_mfma_f32_16x16x32_bf16 v[44:47], v[204:207], v[162:165], v[44:47]
	s_setprio 0
	s_add_u32 s18, s18, 0x80000
	s_addc_u32 s19, s19, 0
	s_mov_b32 m0, s29
	ds_read_b128 v[162:165], v144 offset:32768
	ds_read_b128 v[166:169], v144 offset:33792
	ds_read_b128 v[170:173], v144 offset:34816
	ds_read_b128 v[174:177], v144 offset:35840
	ds_read_b128 v[178:181], v144 offset:36864
	ds_read_b128 v[182:185], v144 offset:37888
	ds_read_b128 v[186:189], v144 offset:38912
	ds_read_b128 v[190:193], v144 offset:39936
	global_load_lds_dwordx4 v136, s[18:19]
	s_mov_b32 m0, s30
	s_nop 0
	global_load_lds_dwordx4 v134, s[18:19]
	s_waitcnt lgkmcnt(8)
	s_barrier
	s_waitcnt lgkmcnt(0)
	s_setprio 1
	s_waitcnt lgkmcnt(0)
	v_mfma_f32_16x16x32_bf16 v[128:131], v[146:149], v[162:165], v[128:131]
	v_mfma_f32_16x16x32_bf16 v[128:131], v[150:153], v[166:169], v[128:131]
	v_mfma_f32_16x16x32_bf16 v[120:123], v[150:153], v[174:177], v[120:123]
	v_mfma_f32_16x16x32_bf16 v[120:123], v[146:149], v[170:173], v[120:123]
	v_mfma_f32_16x16x32_bf16 v[104:107], v[146:149], v[178:181], v[104:107]
	v_mfma_f32_16x16x32_bf16 v[104:107], v[150:153], v[182:185], v[104:107]
	v_mfma_f32_16x16x32_bf16 v[88:91], v[150:153], v[190:193], v[88:91]
	v_mfma_f32_16x16x32_bf16 v[88:91], v[146:149], v[186:189], v[88:91]
	v_mfma_f32_16x16x32_bf16 v[84:87], v[154:157], v[186:189], v[84:87]
	v_mfma_f32_16x16x32_bf16 v[84:87], v[158:161], v[190:193], v[84:87]
	v_mfma_f32_16x16x32_bf16 v[100:103], v[158:161], v[182:185], v[100:103]
	v_mfma_f32_16x16x32_bf16 v[100:103], v[154:157], v[178:181], v[100:103]
	v_mfma_f32_16x16x32_bf16 v[116:119], v[154:157], v[170:173], v[116:119]
	v_mfma_f32_16x16x32_bf16 v[116:119], v[158:161], v[174:177], v[116:119]
	v_mfma_f32_16x16x32_bf16 v[124:127], v[158:161], v[166:169], v[124:127]
	s_barrier
	v_mfma_f32_16x16x32_bf16 v[124:127], v[154:157], v[162:165], v[124:127]
	s_setprio 0
	s_add_i32 s18, 0, 0x1c000
	s_add_i32 s19, s42, s26
	v_add_u32_e32 v145, s18, v142
	v_lshl_add_u64 v[212:213], v[212:213], 0, s[2:3]
	s_mov_b32 m0, s19
	ds_read_b128 v[194:197], v145
	ds_read_b128 v[200:203], v145 offset:1024
	ds_read_b128 v[204:207], v145 offset:2048
	ds_read_b128 v[208:211], v145 offset:3072
	global_load_lds_dwordx4 v[212:213], off
	v_lshl_add_u64 v[212:213], v[214:215], 0, s[2:3]
	s_add_i32 m0, s19, 0x2000
	s_nop 0
	global_load_lds_dwordx4 v[212:213], off
	s_barrier
	s_waitcnt lgkmcnt(0)
	s_setprio 1
	s_waitcnt lgkmcnt(0)
	v_mfma_f32_16x16x32_bf16 v[112:115], v[194:197], v[162:165], v[112:115]
	v_mfma_f32_16x16x32_bf16 v[112:115], v[200:203], v[166:169], v[112:115]
	v_mfma_f32_16x16x32_bf16 v[96:99], v[200:203], v[174:177], v[96:99]
	v_mfma_f32_16x16x32_bf16 v[96:99], v[194:197], v[170:173], v[96:99]
	v_mfma_f32_16x16x32_bf16 v[80:83], v[194:197], v[178:181], v[80:83]
	v_mfma_f32_16x16x32_bf16 v[80:83], v[200:203], v[182:185], v[80:83]
	v_mfma_f32_16x16x32_bf16 v[72:75], v[200:203], v[190:193], v[72:75]
	v_mfma_f32_16x16x32_bf16 v[72:75], v[194:197], v[186:189], v[72:75]
	v_mfma_f32_16x16x32_bf16 v[68:71], v[204:207], v[186:189], v[68:71]
	v_mfma_f32_16x16x32_bf16 v[68:71], v[208:211], v[190:193], v[68:71]
	v_mfma_f32_16x16x32_bf16 v[76:79], v[208:211], v[182:185], v[76:79]
	v_mfma_f32_16x16x32_bf16 v[76:79], v[204:207], v[178:181], v[76:79]
	v_mfma_f32_16x16x32_bf16 v[92:95], v[204:207], v[170:173], v[92:95]
	v_mfma_f32_16x16x32_bf16 v[92:95], v[208:211], v[174:177], v[92:95]
	v_mfma_f32_16x16x32_bf16 v[108:111], v[208:211], v[166:169], v[108:111]
	s_barrier
	v_mfma_f32_16x16x32_bf16 v[108:111], v[204:207], v[162:165], v[108:111]
	s_setprio 0
	s_mov_b32 m0, s31
	v_lshl_add_u64 v[212:213], v[216:217], 0, s[2:3]
	ds_read_b128 v[162:165], v144 offset:49152
	ds_read_b128 v[166:169], v144 offset:50176
	ds_read_b128 v[170:173], v144 offset:51200
	ds_read_b128 v[174:177], v144 offset:52224
	ds_read_b128 v[178:181], v144 offset:53248
	ds_read_b128 v[182:185], v144 offset:54272
	ds_read_b128 v[186:189], v144 offset:55296
	ds_read_b128 v[190:193], v144 offset:56320
	global_load_lds_dwordx4 v[212:213], off
	v_lshl_add_u64 v[212:213], v[218:219], 0, s[2:3]
	s_mov_b32 m0, s33
	s_nop 0
	global_load_lds_dwordx4 v[212:213], off
	s_barrier
	s_waitcnt lgkmcnt(0)
	s_setprio 1
	s_waitcnt lgkmcnt(0)
	v_mfma_f32_16x16x32_bf16 v[64:67], v[146:149], v[162:165], v[64:67]
	v_mfma_f32_16x16x32_bf16 v[64:67], v[150:153], v[166:169], v[64:67]
	v_mfma_f32_16x16x32_bf16 v[56:59], v[150:153], v[174:177], v[56:59]
	v_mfma_f32_16x16x32_bf16 v[56:59], v[146:149], v[170:173], v[56:59]
	v_mfma_f32_16x16x32_bf16 v[40:43], v[146:149], v[178:181], v[40:43]
	v_mfma_f32_16x16x32_bf16 v[40:43], v[150:153], v[182:185], v[40:43]
	v_mfma_f32_16x16x32_bf16 v[24:27], v[150:153], v[190:193], v[24:27]
	v_mfma_f32_16x16x32_bf16 v[24:27], v[146:149], v[186:189], v[24:27]
	v_mfma_f32_16x16x32_bf16 v[20:23], v[154:157], v[186:189], v[20:23]
	v_mfma_f32_16x16x32_bf16 v[20:23], v[158:161], v[190:193], v[20:23]
	v_mfma_f32_16x16x32_bf16 v[36:39], v[158:161], v[182:185], v[36:39]
	v_mfma_f32_16x16x32_bf16 v[36:39], v[154:157], v[178:181], v[36:39]
	v_mfma_f32_16x16x32_bf16 v[52:55], v[154:157], v[170:173], v[52:55]
	v_mfma_f32_16x16x32_bf16 v[52:55], v[158:161], v[174:177], v[52:55]
	v_mfma_f32_16x16x32_bf16 v[60:63], v[158:161], v[166:169], v[60:63]
	s_barrier
	v_mfma_f32_16x16x32_bf16 v[60:63], v[154:157], v[162:165], v[60:63]
	s_setprio 0
	s_add_u32 s16, s16, 0x20080
	s_addc_u32 s17, s17, 0
	s_add_i32 s18, s18, s26
	s_mov_b32 m0, s18
	s_nop 0
	global_load_lds_dwordx4 v2, s[16:17]
	s_add_i32 m0, s18, 0x2000
	s_nop 0
	global_load_lds_dwordx4 v132, s[16:17]
	s_waitcnt vmcnt(6)
	s_barrier
	s_setprio 1
	v_mfma_f32_16x16x32_bf16 v[48:51], v[194:197], v[162:165], v[48:51]
	v_mfma_f32_16x16x32_bf16 v[48:51], v[200:203], v[166:169], v[48:51]
	v_mfma_f32_16x16x32_bf16 v[32:35], v[200:203], v[174:177], v[32:35]
	v_mfma_f32_16x16x32_bf16 v[32:35], v[194:197], v[170:173], v[32:35]
	v_mfma_f32_16x16x32_bf16 v[16:19], v[194:197], v[178:181], v[16:19]
	v_mfma_f32_16x16x32_bf16 v[16:19], v[200:203], v[182:185], v[16:19]
	v_mfma_f32_16x16x32_bf16 v[8:11], v[200:203], v[190:193], v[8:11]
	v_mfma_f32_16x16x32_bf16 v[8:11], v[194:197], v[186:189], v[8:11]
	v_mfma_f32_16x16x32_bf16 v[4:7], v[204:207], v[186:189], v[4:7]
	v_mfma_f32_16x16x32_bf16 v[4:7], v[208:211], v[190:193], v[4:7]
	v_mfma_f32_16x16x32_bf16 v[12:15], v[208:211], v[182:185], v[12:15]
	v_mfma_f32_16x16x32_bf16 v[12:15], v[204:207], v[178:181], v[12:15]
	v_mfma_f32_16x16x32_bf16 v[28:31], v[204:207], v[170:173], v[28:31]
	v_mfma_f32_16x16x32_bf16 v[28:31], v[208:211], v[174:177], v[28:31]
	v_mfma_f32_16x16x32_bf16 v[44:47], v[208:211], v[166:169], v[44:47]
	s_barrier
	v_mfma_f32_16x16x32_bf16 v[44:47], v[204:207], v[162:165], v[44:47]
	s_setprio 0
	s_add_i32 s41, s41, 2
	s_add_u32 s14, s14, 0x100
	s_addc_u32 s15, s15, 0
	s_add_u32 s39, s39, 0x100
	s_addc_u32 s40, s40, 0
	s_cmp_gt_u32 s41, 29
	s_cbranch_scc0 .LBB0_95
	v_lshl_add_u32 v145, s36, 8, v1
	v_lshl_or_b32 v146, s35, 8, v143
	v_ashrrev_i32_e32 v147, 31, v146
	v_mov_b64_e32 v[148:149], s[4:5]
	s_mov_b32 s7, 0x8200
	v_cvt_pk_bf16_f32 v72, v72, v73
	v_cvt_pk_bf16_f32 v73, v74, v75
	v_cvt_pk_bf16_f32 v74, v68, v69
	v_add_u32_e32 v68, 0x80, v145
	v_mad_i64_i32 v[150:151], s[14:15], v145, s7, v[148:149]
	v_lshlrev_b64 v[146:147], 1, v[146:147]
	v_cvt_pk_bf16_f32 v112, v112, v113
	v_cvt_pk_bf16_f32 v113, v114, v115
	v_cvt_pk_bf16_f32 v114, v108, v109
	v_or_b32_e32 v108, 16, v145
	v_mad_i64_i32 v[68:69], s[14:15], v68, s7, v[148:149]
	v_cvt_pk_bf16_f32 v48, v48, v49
	v_cvt_pk_bf16_f32 v49, v50, v51
	v_cvt_pk_bf16_f32 v50, v44, v45
	v_add_u32_e32 v44, 0x90, v145
	v_lshl_add_u64 v[150:151], v[150:151], 0, v[146:147]
	v_cvt_pk_bf16_f32 v115, v110, v111
	v_mad_i64_i32 v[108:109], s[14:15], v108, s7, v[148:149]
	v_cvt_pk_bf16_f32 v96, v96, v97
	v_cvt_pk_bf16_f32 v97, v98, v99
	v_cvt_pk_bf16_f32 v98, v92, v93
	v_or_b32_e32 v92, 32, v145
	v_lshl_add_u64 v[68:69], v[68:69], 0, v[146:147]
	v_cvt_pk_bf16_f32 v51, v46, v47
	v_mad_i64_i32 v[44:45], s[14:15], v44, s7, v[148:149]
	v_cvt_pk_bf16_f32 v32, v32, v33
	v_cvt_pk_bf16_f32 v33, v34, v35
	v_cvt_pk_bf16_f32 v34, v28, v29
	v_add_u32_e32 v28, 0xa0, v145
	global_store_dwordx4 v[150:151], v[112:115], off offset:64 nt
	v_cvt_pk_bf16_f32 v99, v94, v95
	v_mad_i64_i32 v[92:93], s[14:15], v92, s7, v[148:149]
	v_lshl_add_u64 v[112:113], v[108:109], 0, v[146:147]
	v_cvt_pk_bf16_f32 v80, v80, v81
	v_cvt_pk_bf16_f32 v81, v82, v83
	v_cvt_pk_bf16_f32 v82, v76, v77
	v_or_b32_e32 v76, 48, v145
	global_store_dwordx4 v[68:69], v[48:51], off offset:64 nt
	v_cvt_pk_bf16_f32 v35, v30, v31
	v_mad_i64_i32 v[28:29], s[14:15], v28, s7, v[148:149]
	v_lshl_add_u64 v[48:49], v[44:45], 0, v[146:147]
	v_cvt_pk_bf16_f32 v16, v16, v17
	v_cvt_pk_bf16_f32 v17, v18, v19
	v_cvt_pk_bf16_f32 v18, v12, v13
	v_add_u32_e32 v12, 0xb0, v145
	global_store_dwordx4 v[112:113], v[96:99], off offset:64 nt
	v_cvt_pk_bf16_f32 v83, v78, v79
	v_mad_i64_i32 v[76:77], s[14:15], v76, s7, v[148:149]
	v_lshl_add_u64 v[96:97], v[92:93], 0, v[146:147]
	global_store_dwordx4 v[48:49], v[32:35], off offset:64 nt
	v_cvt_pk_bf16_f32 v19, v14, v15
	v_mad_i64_i32 v[12:13], s[14:15], v12, s7, v[148:149]
	v_lshl_add_u64 v[32:33], v[28:29], 0, v[146:147]
	v_cvt_pk_bf16_f32 v128, v128, v129
	v_cvt_pk_bf16_f32 v129, v130, v131
	v_cvt_pk_bf16_f32 v130, v124, v125
	v_cvt_pk_bf16_f32 v131, v126, v127
	v_cvt_pk_bf16_f32 v108, v120, v121
	v_cvt_pk_bf16_f32 v109, v122, v123
	v_cvt_pk_bf16_f32 v110, v116, v117
	v_cvt_pk_bf16_f32 v111, v118, v119
	v_cvt_pk_bf16_f32 v92, v104, v105
	v_cvt_pk_bf16_f32 v93, v106, v107
	v_cvt_pk_bf16_f32 v94, v100, v101
	v_cvt_pk_bf16_f32 v95, v102, v103
	global_store_dwordx4 v[96:97], v[80:83], off offset:64 nt
	v_cvt_pk_bf16_f32 v78, v84, v85
	v_cvt_pk_bf16_f32 v79, v86, v87
	v_lshl_add_u64 v[80:81], v[76:77], 0, v[146:147]
	v_cvt_pk_bf16_f32 v76, v88, v89
	v_cvt_pk_bf16_f32 v77, v90, v91
	v_cvt_pk_bf16_f32 v75, v70, v71
	v_cvt_pk_bf16_f32 v64, v64, v65
	v_cvt_pk_bf16_f32 v65, v66, v67
	v_cvt_pk_bf16_f32 v66, v60, v61
	v_cvt_pk_bf16_f32 v67, v62, v63
	v_cvt_pk_bf16_f32 v44, v56, v57
	v_cvt_pk_bf16_f32 v45, v58, v59
	v_cvt_pk_bf16_f32 v46, v52, v53
	v_cvt_pk_bf16_f32 v47, v54, v55
	v_cvt_pk_bf16_f32 v28, v40, v41
	v_cvt_pk_bf16_f32 v29, v42, v43
	v_cvt_pk_bf16_f32 v30, v36, v37
	v_cvt_pk_bf16_f32 v31, v38, v39
	global_store_dwordx4 v[32:33], v[16:19], off offset:64 nt
	v_cvt_pk_bf16_f32 v14, v20, v21
	v_cvt_pk_bf16_f32 v15, v22, v23
	v_lshl_add_u64 v[16:17], v[12:13], 0, v[146:147]
	v_cvt_pk_bf16_f32 v12, v24, v25
	v_cvt_pk_bf16_f32 v13, v26, v27
	v_cvt_pk_bf16_f32 v8, v8, v9
	v_cvt_pk_bf16_f32 v9, v10, v11
	v_cvt_pk_bf16_f32 v10, v4, v5
	v_cvt_pk_bf16_f32 v11, v6, v7
	s_and_b64 vcc, exec, s[0:1]
	s_mov_b32 s35, s6
	s_mov_b32 s36, s8
	s_mov_b64 s[16:17], s[12:13]
	s_mov_b64 s[14:15], s[10:11]
	global_store_dwordx4 v[150:151], v[128:131], off nt
	global_store_dwordx4 v[112:113], v[108:111], off nt
	global_store_dwordx4 v[96:97], v[92:95], off nt
	global_store_dwordx4 v[80:81], v[76:79], off nt
	global_store_dwordx4 v[80:81], v[72:75], off offset:64 nt
	global_store_dwordx4 v[68:69], v[64:67], off nt
	global_store_dwordx4 v[48:49], v[44:47], off nt
	global_store_dwordx4 v[32:33], v[28:31], off nt
	global_store_dwordx4 v[16:17], v[12:15], off nt
	global_store_dwordx4 v[16:17], v[8:11], off offset:64 nt
	s_cbranch_vccz .LBB0_92
	s_waitcnt vmcnt(0)
	s_cmpk_gt_u32 s21, 0xff
	s_cbranch_scc1 .LBB0_99
	s_barrier

.LBB0_236:
	s_add_u32 s16, s14, 0xfffe0080
	s_addc_u32 s17, s15, -1
	s_add_i32 s41, 0, 0x10000
	v_add_u32_e32 v145, s41, v142
	ds_read_b128 v[146:149], v145
	ds_read_b128 v[150:153], v145 offset:1024
	ds_read_b128 v[154:157], v145 offset:2048
	ds_read_b128 v[158:161], v145 offset:3072
	s_cmp_eq_u32 s40, 4
	s_cselect_b32 s19, s9, s17
	s_cselect_b32 s18, s36, s16
	s_cselect_b32 s17, s7, s39
	s_cselect_b32 s16, s37, s38
	s_add_i32 m0, s26, 0xc000
	ds_read_b128 v[162:165], v144
	ds_read_b128 v[166:169], v144 offset:1024
	ds_read_b128 v[170:173], v144 offset:2048
	ds_read_b128 v[174:177], v144 offset:3072
	ds_read_b128 v[178:181], v144 offset:4096
	ds_read_b128 v[182:185], v144 offset:5120
	ds_read_b128 v[186:189], v144 offset:6144
	ds_read_b128 v[190:193], v144 offset:7168
	global_load_lds_dwordx4 v138, s[14:15]
	s_add_i32 m0, s26, 0xe000
	s_nop 0
	global_load_lds_dwordx4 v140, s[14:15]
	s_waitcnt lgkmcnt(8)
	s_barrier
	s_waitcnt lgkmcnt(0)
	s_setprio 1
	s_waitcnt lgkmcnt(0)
	v_mfma_f32_16x16x32_bf16 v[128:131], v[146:149], v[162:165], v[128:131]
	v_mfma_f32_16x16x32_bf16 v[128:131], v[150:153], v[166:169], v[128:131]
	v_mfma_f32_16x16x32_bf16 v[120:123], v[150:153], v[174:177], v[120:123]
	v_mfma_f32_16x16x32_bf16 v[120:123], v[146:149], v[170:173], v[120:123]
	v_mfma_f32_16x16x32_bf16 v[104:107], v[146:149], v[178:181], v[104:107]
	v_mfma_f32_16x16x32_bf16 v[104:107], v[150:153], v[182:185], v[104:107]
	v_mfma_f32_16x16x32_bf16 v[88:91], v[150:153], v[190:193], v[88:91]
	v_mfma_f32_16x16x32_bf16 v[88:91], v[146:149], v[186:189], v[88:91]
	v_mfma_f32_16x16x32_bf16 v[84:87], v[154:157], v[186:189], v[84:87]
	v_mfma_f32_16x16x32_bf16 v[84:87], v[158:161], v[190:193], v[84:87]
	v_mfma_f32_16x16x32_bf16 v[100:103], v[158:161], v[182:185], v[100:103]
	v_mfma_f32_16x16x32_bf16 v[100:103], v[154:157], v[178:181], v[100:103]
	v_mfma_f32_16x16x32_bf16 v[116:119], v[154:157], v[170:173], v[116:119]
	v_mfma_f32_16x16x32_bf16 v[116:119], v[158:161], v[174:177], v[116:119]
	v_mfma_f32_16x16x32_bf16 v[124:127], v[158:161], v[166:169], v[124:127]
	s_barrier
	v_mfma_f32_16x16x32_bf16 v[124:127], v[154:157], v[162:165], v[124:127]
	s_setprio 0
	s_add_i32 s44, 0, 0x14000
	s_add_i32 s41, s41, s25
	v_add_u32_e32 v145, s44, v142
	v_lshl_add_u64 v[212:213], s[16:17], 0, v[2:3]
	s_mov_b32 m0, s41
	ds_read_b128 v[194:197], v145
	ds_read_b128 v[200:203], v145 offset:1024
	ds_read_b128 v[204:207], v145 offset:2048
	ds_read_b128 v[208:211], v145 offset:3072
	global_load_lds_dwordx4 v[212:213], off
	v_lshl_add_u64 v[214:215], s[16:17], 0, v[132:133]
	s_add_i32 m0, s41, 0x2000
	s_nop 0
	global_load_lds_dwordx4 v[214:215], off
	s_barrier
	s_waitcnt lgkmcnt(0)
	s_setprio 1
	s_waitcnt lgkmcnt(0)
	v_mfma_f32_16x16x32_bf16 v[112:115], v[194:197], v[162:165], v[112:115]
	v_mfma_f32_16x16x32_bf16 v[112:115], v[200:203], v[166:169], v[112:115]
	v_mfma_f32_16x16x32_bf16 v[96:99], v[200:203], v[174:177], v[96:99]
	v_mfma_f32_16x16x32_bf16 v[96:99], v[194:197], v[170:173], v[96:99]
	v_mfma_f32_16x16x32_bf16 v[80:83], v[194:197], v[178:181], v[80:83]
	v_mfma_f32_16x16x32_bf16 v[80:83], v[200:203], v[182:185], v[80:83]
	v_mfma_f32_16x16x32_bf16 v[72:75], v[200:203], v[190:193], v[72:75]
	v_mfma_f32_16x16x32_bf16 v[72:75], v[194:197], v[186:189], v[72:75]
	v_mfma_f32_16x16x32_bf16 v[68:71], v[204:207], v[186:189], v[68:71]
	v_mfma_f32_16x16x32_bf16 v[68:71], v[208:211], v[190:193], v[68:71]
	v_mfma_f32_16x16x32_bf16 v[76:79], v[208:211], v[182:185], v[76:79]
	v_mfma_f32_16x16x32_bf16 v[76:79], v[204:207], v[178:181], v[76:79]
	v_mfma_f32_16x16x32_bf16 v[92:95], v[204:207], v[170:173], v[92:95]
	v_mfma_f32_16x16x32_bf16 v[92:95], v[208:211], v[174:177], v[92:95]
	v_mfma_f32_16x16x32_bf16 v[108:111], v[208:211], v[166:169], v[108:111]
	s_barrier
	v_mfma_f32_16x16x32_bf16 v[108:111], v[204:207], v[162:165], v[108:111]
	s_setprio 0
	s_mov_b32 m0, s26
	v_lshl_add_u64 v[216:217], s[18:19], 0, v[136:137]
	ds_read_b128 v[162:165], v144 offset:16384
	ds_read_b128 v[166:169], v144 offset:17408
	ds_read_b128 v[170:173], v144 offset:18432
	ds_read_b128 v[174:177], v144 offset:19456
	ds_read_b128 v[178:181], v144 offset:20480
	ds_read_b128 v[182:185], v144 offset:21504
	ds_read_b128 v[186:189], v144 offset:22528
	ds_read_b128 v[190:193], v144 offset:23552
	global_load_lds_dwordx4 v[216:217], off
	v_lshl_add_u64 v[218:219], s[18:19], 0, v[134:135]
	s_mov_b32 m0, s27
	s_nop 0
	global_load_lds_dwordx4 v[218:219], off
	s_waitcnt vmcnt(10)
	s_barrier
	s_waitcnt lgkmcnt(0)
	s_setprio 1
	s_waitcnt lgkmcnt(0)
	v_mfma_f32_16x16x32_bf16 v[64:67], v[146:149], v[162:165], v[64:67]
	v_mfma_f32_16x16x32_bf16 v[64:67], v[150:153], v[166:169], v[64:67]
	v_mfma_f32_16x16x32_bf16 v[56:59], v[150:153], v[174:177], v[56:59]
	v_mfma_f32_16x16x32_bf16 v[56:59], v[146:149], v[170:173], v[56:59]
	v_mfma_f32_16x16x32_bf16 v[40:43], v[146:149], v[178:181], v[40:43]
	v_mfma_f32_16x16x32_bf16 v[40:43], v[150:153], v[182:185], v[40:43]
	v_mfma_f32_16x16x32_bf16 v[24:27], v[150:153], v[190:193], v[24:27]
	v_mfma_f32_16x16x32_bf16 v[24:27], v[146:149], v[186:189], v[24:27]
	v_mfma_f32_16x16x32_bf16 v[20:23], v[154:157], v[186:189], v[20:23]
	v_mfma_f32_16x16x32_bf16 v[20:23], v[158:161], v[190:193], v[20:23]
	v_mfma_f32_16x16x32_bf16 v[36:39], v[158:161], v[182:185], v[36:39]
	v_mfma_f32_16x16x32_bf16 v[36:39], v[154:157], v[178:181], v[36:39]
	v_mfma_f32_16x16x32_bf16 v[52:55], v[154:157], v[170:173], v[52:55]
	v_mfma_f32_16x16x32_bf16 v[52:55], v[158:161], v[174:177], v[52:55]
	v_mfma_f32_16x16x32_bf16 v[60:63], v[158:161], v[166:169], v[60:63]
	s_barrier
	v_mfma_f32_16x16x32_bf16 v[60:63], v[154:157], v[162:165], v[60:63]
	s_setprio 0
	s_add_u32 s42, s16, 0x8000
	s_addc_u32 s43, s17, 0
	s_add_i32 s41, s44, s25
	s_mov_b32 m0, s41
	s_nop 0
	global_load_lds_dwordx4 v2, s[42:43]
	s_add_i32 m0, s41, 0x2000
	s_nop 0
	global_load_lds_dwordx4 v132, s[42:43]
	s_add_i32 s41, 0, 0x18000
	v_add_u32_e32 v145, s41, v142
	ds_read_b128 v[146:149], v145
	ds_read_b128 v[150:153], v145 offset:1024
	ds_read_b128 v[154:157], v145 offset:2048
	ds_read_b128 v[158:161], v145 offset:3072
	s_waitcnt vmcnt(6)
	s_barrier
	s_setprio 1
	v_mfma_f32_16x16x32_bf16 v[48:51], v[194:197], v[162:165], v[48:51]
	v_mfma_f32_16x16x32_bf16 v[48:51], v[200:203], v[166:169], v[48:51]
	v_mfma_f32_16x16x32_bf16 v[32:35], v[200:203], v[174:177], v[32:35]
	v_mfma_f32_16x16x32_bf16 v[32:35], v[194:197], v[170:173], v[32:35]
	v_mfma_f32_16x16x32_bf16 v[16:19], v[194:197], v[178:181], v[16:19]
	v_mfma_f32_16x16x32_bf16 v[16:19], v[200:203], v[182:185], v[16:19]
	v_mfma_f32_16x16x32_bf16 v[8:11], v[200:203], v[190:193], v[8:11]
	v_mfma_f32_16x16x32_bf16 v[8:11], v[194:197], v[186:189], v[8:11]
	v_mfma_f32_16x16x32_bf16 v[4:7], v[204:207], v[186:189], v[4:7]
	v_mfma_f32_16x16x32_bf16 v[4:7], v[208:211], v[190:193], v[4:7]
	v_mfma_f32_16x16x32_bf16 v[12:15], v[208:211], v[182:185], v[12:15]
	v_mfma_f32_16x16x32_bf16 v[12:15], v[204:207], v[178:181], v[12:15]
	v_mfma_f32_16x16x32_bf16 v[28:31], v[204:207], v[170:173], v[28:31]
	v_mfma_f32_16x16x32_bf16 v[28:31], v[208:211], v[174:177], v[28:31]
	v_mfma_f32_16x16x32_bf16 v[44:47], v[208:211], v[166:169], v[44:47]
	s_barrier
	v_mfma_f32_16x16x32_bf16 v[44:47], v[204:207], v[162:165], v[44:47]
	s_setprio 0
	s_add_u32 s18, s18, 0x20000
	s_addc_u32 s19, s19, 0
	s_mov_b32 m0, s28
	ds_read_b128 v[162:165], v144 offset:32768
	ds_read_b128 v[166:169], v144 offset:33792
	ds_read_b128 v[170:173], v144 offset:34816
	ds_read_b128 v[174:177], v144 offset:35840
	ds_read_b128 v[178:181], v144 offset:36864
	ds_read_b128 v[182:185], v144 offset:37888
	ds_read_b128 v[186:189], v144 offset:38912
	ds_read_b128 v[190:193], v144 offset:39936
	global_load_lds_dwordx4 v136, s[18:19]
	s_mov_b32 m0, s29
	s_nop 0
	global_load_lds_dwordx4 v134, s[18:19]
	s_waitcnt lgkmcnt(8)
	s_barrier
	s_waitcnt lgkmcnt(0)
	s_setprio 1
	s_waitcnt lgkmcnt(0)
	v_mfma_f32_16x16x32_bf16 v[128:131], v[146:149], v[162:165], v[128:131]
	v_mfma_f32_16x16x32_bf16 v[128:131], v[150:153], v[166:169], v[128:131]
	v_mfma_f32_16x16x32_bf16 v[120:123], v[150:153], v[174:177], v[120:123]
	v_mfma_f32_16x16x32_bf16 v[120:123], v[146:149], v[170:173], v[120:123]
	v_mfma_f32_16x16x32_bf16 v[104:107], v[146:149], v[178:181], v[104:107]
	v_mfma_f32_16x16x32_bf16 v[104:107], v[150:153], v[182:185], v[104:107]
	v_mfma_f32_16x16x32_bf16 v[88:91], v[150:153], v[190:193], v[88:91]
	v_mfma_f32_16x16x32_bf16 v[88:91], v[146:149], v[186:189], v[88:91]
	v_mfma_f32_16x16x32_bf16 v[84:87], v[154:157], v[186:189], v[84:87]
	v_mfma_f32_16x16x32_bf16 v[84:87], v[158:161], v[190:193], v[84:87]
	v_mfma_f32_16x16x32_bf16 v[100:103], v[158:161], v[182:185], v[100:103]
	v_mfma_f32_16x16x32_bf16 v[100:103], v[154:157], v[178:181], v[100:103]
	v_mfma_f32_16x16x32_bf16 v[116:119], v[154:157], v[170:173], v[116:119]
	v_mfma_f32_16x16x32_bf16 v[116:119], v[158:161], v[174:177], v[116:119]
	v_mfma_f32_16x16x32_bf16 v[124:127], v[158:161], v[166:169], v[124:127]
	s_barrier
	v_mfma_f32_16x16x32_bf16 v[124:127], v[154:157], v[162:165], v[124:127]
	s_setprio 0
	s_add_i32 s18, 0, 0x1c000
	s_add_i32 s19, s41, s25
	v_add_u32_e32 v145, s18, v142
	v_lshl_add_u64 v[212:213], v[212:213], 0, s[2:3]
	s_mov_b32 m0, s19
	ds_read_b128 v[194:197], v145
	ds_read_b128 v[200:203], v145 offset:1024
	ds_read_b128 v[204:207], v145 offset:2048
	ds_read_b128 v[208:211], v145 offset:3072
	global_load_lds_dwordx4 v[212:213], off
	v_lshl_add_u64 v[212:213], v[214:215], 0, s[2:3]
	s_add_i32 m0, s19, 0x2000
	s_nop 0
	global_load_lds_dwordx4 v[212:213], off
	s_barrier
	s_waitcnt lgkmcnt(0)
	s_setprio 1
	s_waitcnt lgkmcnt(0)
	v_mfma_f32_16x16x32_bf16 v[112:115], v[194:197], v[162:165], v[112:115]
	v_mfma_f32_16x16x32_bf16 v[112:115], v[200:203], v[166:169], v[112:115]
	v_mfma_f32_16x16x32_bf16 v[96:99], v[200:203], v[174:177], v[96:99]
	v_mfma_f32_16x16x32_bf16 v[96:99], v[194:197], v[170:173], v[96:99]
	v_mfma_f32_16x16x32_bf16 v[80:83], v[194:197], v[178:181], v[80:83]
	v_mfma_f32_16x16x32_bf16 v[80:83], v[200:203], v[182:185], v[80:83]
	v_mfma_f32_16x16x32_bf16 v[72:75], v[200:203], v[190:193], v[72:75]
	v_mfma_f32_16x16x32_bf16 v[72:75], v[194:197], v[186:189], v[72:75]
	v_mfma_f32_16x16x32_bf16 v[68:71], v[204:207], v[186:189], v[68:71]
	v_mfma_f32_16x16x32_bf16 v[68:71], v[208:211], v[190:193], v[68:71]
	v_mfma_f32_16x16x32_bf16 v[76:79], v[208:211], v[182:185], v[76:79]
	v_mfma_f32_16x16x32_bf16 v[76:79], v[204:207], v[178:181], v[76:79]
	v_mfma_f32_16x16x32_bf16 v[92:95], v[204:207], v[170:173], v[92:95]
	v_mfma_f32_16x16x32_bf16 v[92:95], v[208:211], v[174:177], v[92:95]
	v_mfma_f32_16x16x32_bf16 v[108:111], v[208:211], v[166:169], v[108:111]
	s_barrier
	v_mfma_f32_16x16x32_bf16 v[108:111], v[204:207], v[162:165], v[108:111]
	s_setprio 0
	s_mov_b32 m0, s30
	v_lshl_add_u64 v[212:213], v[216:217], 0, s[2:3]
	ds_read_b128 v[162:165], v144 offset:49152
	ds_read_b128 v[166:169], v144 offset:50176
	ds_read_b128 v[170:173], v144 offset:51200
	ds_read_b128 v[174:177], v144 offset:52224
	ds_read_b128 v[178:181], v144 offset:53248
	ds_read_b128 v[182:185], v144 offset:54272
	ds_read_b128 v[186:189], v144 offset:55296
	ds_read_b128 v[190:193], v144 offset:56320
	global_load_lds_dwordx4 v[212:213], off
	v_lshl_add_u64 v[212:213], v[218:219], 0, s[2:3]
	s_mov_b32 m0, s31
	s_nop 0
	global_load_lds_dwordx4 v[212:213], off
	s_barrier
	s_waitcnt lgkmcnt(0)
	s_setprio 1
	s_waitcnt lgkmcnt(0)
	v_mfma_f32_16x16x32_bf16 v[64:67], v[146:149], v[162:165], v[64:67]
	v_mfma_f32_16x16x32_bf16 v[64:67], v[150:153], v[166:169], v[64:67]
	v_mfma_f32_16x16x32_bf16 v[56:59], v[150:153], v[174:177], v[56:59]
	v_mfma_f32_16x16x32_bf16 v[56:59], v[146:149], v[170:173], v[56:59]
	v_mfma_f32_16x16x32_bf16 v[40:43], v[146:149], v[178:181], v[40:43]
	v_mfma_f32_16x16x32_bf16 v[40:43], v[150:153], v[182:185], v[40:43]
	v_mfma_f32_16x16x32_bf16 v[24:27], v[150:153], v[190:193], v[24:27]
	v_mfma_f32_16x16x32_bf16 v[24:27], v[146:149], v[186:189], v[24:27]
	v_mfma_f32_16x16x32_bf16 v[20:23], v[154:157], v[186:189], v[20:23]
	v_mfma_f32_16x16x32_bf16 v[20:23], v[158:161], v[190:193], v[20:23]
	v_mfma_f32_16x16x32_bf16 v[36:39], v[158:161], v[182:185], v[36:39]
	v_mfma_f32_16x16x32_bf16 v[36:39], v[154:157], v[178:181], v[36:39]
	v_mfma_f32_16x16x32_bf16 v[52:55], v[154:157], v[170:173], v[52:55]
	v_mfma_f32_16x16x32_bf16 v[52:55], v[158:161], v[174:177], v[52:55]
	v_mfma_f32_16x16x32_bf16 v[60:63], v[158:161], v[166:169], v[60:63]
	s_barrier
	v_mfma_f32_16x16x32_bf16 v[60:63], v[154:157], v[162:165], v[60:63]
	s_setprio 0
	s_add_u32 s16, s16, 0x8080
	s_addc_u32 s17, s17, 0
	s_add_i32 s18, s18, s25
	s_mov_b32 m0, s18
	s_nop 0
	global_load_lds_dwordx4 v2, s[16:17]
	s_add_i32 m0, s18, 0x2000
	s_nop 0
	global_load_lds_dwordx4 v132, s[16:17]
	s_waitcnt vmcnt(6)
	s_barrier
	s_setprio 1
	v_mfma_f32_16x16x32_bf16 v[48:51], v[194:197], v[162:165], v[48:51]
	v_mfma_f32_16x16x32_bf16 v[48:51], v[200:203], v[166:169], v[48:51]
	v_mfma_f32_16x16x32_bf16 v[32:35], v[200:203], v[174:177], v[32:35]
	v_mfma_f32_16x16x32_bf16 v[32:35], v[194:197], v[170:173], v[32:35]
	v_mfma_f32_16x16x32_bf16 v[16:19], v[194:197], v[178:181], v[16:19]
	v_mfma_f32_16x16x32_bf16 v[16:19], v[200:203], v[182:185], v[16:19]
	v_mfma_f32_16x16x32_bf16 v[8:11], v[200:203], v[190:193], v[8:11]
	v_mfma_f32_16x16x32_bf16 v[8:11], v[194:197], v[186:189], v[8:11]
	v_mfma_f32_16x16x32_bf16 v[4:7], v[204:207], v[186:189], v[4:7]
	v_mfma_f32_16x16x32_bf16 v[4:7], v[208:211], v[190:193], v[4:7]
	v_mfma_f32_16x16x32_bf16 v[12:15], v[208:211], v[182:185], v[12:15]
	v_mfma_f32_16x16x32_bf16 v[12:15], v[204:207], v[178:181], v[12:15]
	v_mfma_f32_16x16x32_bf16 v[28:31], v[204:207], v[170:173], v[28:31]
	v_mfma_f32_16x16x32_bf16 v[28:31], v[208:211], v[174:177], v[28:31]
	v_mfma_f32_16x16x32_bf16 v[44:47], v[208:211], v[166:169], v[44:47]
	s_barrier
	v_mfma_f32_16x16x32_bf16 v[44:47], v[204:207], v[162:165], v[44:47]
	s_setprio 0
	s_add_i32 s40, s40, 2
	s_add_u32 s14, s14, 0x100
	s_addc_u32 s15, s15, 0
	s_add_u32 s38, s38, 0x100
	s_addc_u32 s39, s39, 0
	s_cmp_gt_u32 s40, 5
	s_cbranch_scc0 .LBB0_236
	v_lshl_add_u32 v146, s35, 8, v1
	v_lshl_or_b32 v148, s34, 8, v143
	v_ashrrev_i32_e32 v147, 31, v146
	v_ashrrev_i32_e32 v149, 31, v148
	v_lshlrev_b64 v[150:151], 12, v[146:147]
	v_lshl_add_u64 v[150:151], s[4:5], 0, v[150:151]
	v_lshlrev_b64 v[148:149], 1, v[148:149]
	v_lshl_add_u64 v[150:151], v[150:151], 0, v[148:149]
	s_mov_b32 s7, 0x80000
	s_mov_b64 s[14:15], 0x80000
	v_cvt_pk_bf16_f32 v64, v64, v65
	v_cvt_pk_bf16_f32 v65, v66, v67
	v_cvt_pk_bf16_f32 v66, v60, v61
	v_add_co_u32_e32 v60, vcc, s7, v150
	v_cvt_pk_bf16_f32 v72, v72, v73
	v_cvt_pk_bf16_f32 v73, v74, v75
	v_cvt_pk_bf16_f32 v74, v68, v69
	v_lshl_add_u64 v[68:69], v[150:151], 0, s[14:15]
	v_addc_co_u32_e32 v61, vcc, 0, v151, vcc
	v_cvt_pk_bf16_f32 v48, v48, v49
	v_cvt_pk_bf16_f32 v49, v50, v51
	v_cvt_pk_bf16_f32 v50, v44, v45
	v_cvt_pk_bf16_f32 v51, v46, v47
	s_mov_b32 s7, 0x90000
	v_cvt_pk_bf16_f32 v112, v112, v113
	v_cvt_pk_bf16_f32 v113, v114, v115
	v_cvt_pk_bf16_f32 v114, v108, v109
	v_or_b32_e32 v108, 16, v146
	global_store_dwordx4 v[68:69], v[48:51], off offset:64
	s_mov_b64 s[14:15], 0x90000
	v_ashrrev_i32_e32 v109, 31, v108
	v_add_co_u32_e32 v50, vcc, s7, v150
	v_cvt_pk_bf16_f32 v96, v96, v97
	v_cvt_pk_bf16_f32 v97, v98, v99
	v_cvt_pk_bf16_f32 v98, v92, v93
	v_or_b32_e32 v92, 32, v146
	v_lshl_add_u64 v[48:49], v[150:151], 0, s[14:15]
	v_addc_co_u32_e32 v51, vcc, 0, v151, vcc
	v_cvt_pk_bf16_f32 v32, v32, v33
	v_cvt_pk_bf16_f32 v33, v34, v35
	v_cvt_pk_bf16_f32 v34, v28, v29
	v_cvt_pk_bf16_f32 v35, v30, v31
	s_mov_b32 s7, 0xa0000
	v_lshlrev_b64 v[108:109], 12, v[108:109]
	v_ashrrev_i32_e32 v93, 31, v92
	v_cvt_pk_bf16_f32 v80, v80, v81
	v_cvt_pk_bf16_f32 v81, v82, v83
	v_cvt_pk_bf16_f32 v82, v76, v77
	v_or_b32_e32 v76, 48, v146
	global_store_dwordx4 v[48:49], v[32:35], off offset:64
	s_mov_b64 s[14:15], 0xa0000
	v_cvt_pk_bf16_f32 v115, v110, v111
	v_add_co_u32_e32 v34, vcc, s7, v150
	v_lshl_add_u64 v[108:109], s[4:5], 0, v[108:109]
	v_lshlrev_b64 v[92:93], 12, v[92:93]
	v_ashrrev_i32_e32 v77, 31, v76
	v_lshl_add_u64 v[32:33], v[150:151], 0, s[14:15]
	v_addc_co_u32_e32 v35, vcc, 0, v151, vcc
	v_cvt_pk_bf16_f32 v16, v16, v17
	v_cvt_pk_bf16_f32 v17, v18, v19
	v_cvt_pk_bf16_f32 v18, v12, v13
	v_cvt_pk_bf16_f32 v19, v14, v15
	s_mov_b32 s7, 0xb0000
	global_store_dwordx4 v[150:151], v[112:115], off offset:64
	v_cvt_pk_bf16_f32 v99, v94, v95
	v_lshl_add_u64 v[92:93], s[4:5], 0, v[92:93]
	v_lshl_add_u64 v[112:113], v[108:109], 0, v[148:149]
	v_lshlrev_b64 v[76:77], 12, v[76:77]
	global_store_dwordx4 v[32:33], v[16:19], off offset:64
	global_store_dwordx4 v[112:113], v[96:99], off offset:64
	v_cvt_pk_bf16_f32 v83, v78, v79
	v_add_co_u32_e32 v18, vcc, s7, v150
	v_lshl_add_u64 v[96:97], v[92:93], 0, v[148:149]
	v_lshl_add_u64 v[76:77], s[4:5], 0, v[76:77]
	s_mov_b64 s[14:15], 0xb0000
	v_addc_co_u32_e32 v19, vcc, 0, v151, vcc
	v_cvt_pk_bf16_f32 v128, v128, v129
	v_cvt_pk_bf16_f32 v129, v130, v131
	v_cvt_pk_bf16_f32 v130, v124, v125
	v_cvt_pk_bf16_f32 v131, v126, v127
	v_cvt_pk_bf16_f32 v108, v120, v121
	v_cvt_pk_bf16_f32 v109, v122, v123
	v_cvt_pk_bf16_f32 v110, v116, v117
	v_cvt_pk_bf16_f32 v111, v118, v119
	v_cvt_pk_bf16_f32 v92, v104, v105
	v_cvt_pk_bf16_f32 v93, v106, v107
	v_cvt_pk_bf16_f32 v94, v100, v101
	v_cvt_pk_bf16_f32 v95, v102, v103
	global_store_dwordx4 v[96:97], v[80:83], off offset:64
	v_cvt_pk_bf16_f32 v78, v84, v85
	v_cvt_pk_bf16_f32 v79, v86, v87
	v_lshl_add_u64 v[80:81], v[76:77], 0, v[148:149]
	v_cvt_pk_bf16_f32 v76, v88, v89
	v_cvt_pk_bf16_f32 v77, v90, v91
	v_cvt_pk_bf16_f32 v75, v70, v71
	v_cvt_pk_bf16_f32 v67, v62, v63
	v_cvt_pk_bf16_f32 v44, v56, v57
	v_cvt_pk_bf16_f32 v45, v58, v59
	v_cvt_pk_bf16_f32 v46, v52, v53
	v_cvt_pk_bf16_f32 v47, v54, v55
	v_cvt_pk_bf16_f32 v28, v40, v41
	v_cvt_pk_bf16_f32 v29, v42, v43
	v_cvt_pk_bf16_f32 v30, v36, v37
	v_cvt_pk_bf16_f32 v31, v38, v39
	v_lshl_add_u64 v[16:17], v[150:151], 0, s[14:15]
	v_cvt_pk_bf16_f32 v12, v24, v25
	v_cvt_pk_bf16_f32 v13, v26, v27
	v_cvt_pk_bf16_f32 v14, v20, v21
	v_cvt_pk_bf16_f32 v15, v22, v23
	v_cvt_pk_bf16_f32 v8, v8, v9
	v_cvt_pk_bf16_f32 v9, v10, v11
	v_cvt_pk_bf16_f32 v10, v4, v5
	v_cvt_pk_bf16_f32 v11, v6, v7
	s_and_b64 vcc, exec, s[0:1]
	s_mov_b32 s34, s6
	s_mov_b32 s35, s8
	s_mov_b64 s[16:17], s[12:13]
	s_mov_b64 s[14:15], s[10:11]
	global_store_dwordx4 v[150:151], v[128:131], off
	global_store_dwordx4 v[112:113], v[108:111], off
	global_store_dwordx4 v[96:97], v[92:95], off
	global_store_dwordx4 v[80:81], v[76:79], off
	global_store_dwordx4 v[80:81], v[72:75], off offset:64
	global_store_dwordx4 v[60:61], v[64:67], off
	global_store_dwordx4 v[50:51], v[44:47], off
	global_store_dwordx4 v[34:35], v[28:31], off
	global_store_dwordx4 v[18:19], v[12:15], off
	global_store_dwordx4 v[16:17], v[8:11], off offset:64
	s_cbranch_vccz .LBB0_233
	s_waitcnt vmcnt(0)
	s_cmpk_gt_u32 s20, 0xff
	s_cbranch_scc1 .LBB0_240
	s_barrier

.LBB0_816:
	s_add_u32 s18, s16, 0x100
	s_addc_u32 s19, s17, 0
	s_cmpk_eq_i32 s14, 0x2e00
	s_cselect_b32 s23, s1, s19
	s_cselect_b32 s22, s0, s18
	s_cselect_b32 s21, s7, s42
	s_cselect_b32 s20, s6, s41
	s_add_i32 s33, 0, 0x10000
	v_add_u32_e32 v2, s33, v200
	ds_read_b128 v[62:65], v2
	ds_read_b128 v[74:77], v2 offset:1024
	ds_read_b128 v[82:85], v2 offset:2048
	ds_read_b128 v[94:97], v2 offset:3072
	s_add_i32 m0, s30, 0xc000
	ds_read_b128 v[106:109], v202
	ds_read_b128 v[118:121], v202 offset:1024
	ds_read_b128 v[130:133], v202 offset:2048
	ds_read_b128 v[142:145], v202 offset:3072
	ds_read_b128 v[150:153], v202 offset:4096
	ds_read_b128 v[162:165], v202 offset:5120
	ds_read_b128 v[174:177], v202 offset:6144
	ds_read_b128 v[178:181], v202 offset:7168
	global_load_lds_dwordx4 v212, s[16:17]
	s_add_i32 m0, s30, 0xe000
	s_nop 0
	global_load_lds_dwordx4 v214, s[16:17]
	s_waitcnt lgkmcnt(8)
	s_barrier
	s_waitcnt lgkmcnt(0)
	s_setprio 1
	s_waitcnt lgkmcnt(0)
	v_mfma_f32_16x16x32_bf16 v[170:173], v[62:65], v[106:109], v[170:173]
	v_mfma_f32_16x16x32_bf16 v[170:173], v[74:77], v[118:121], v[170:173]
	v_mfma_f32_16x16x32_bf16 v[146:149], v[74:77], v[142:145], v[146:149]
	v_mfma_f32_16x16x32_bf16 v[146:149], v[62:65], v[130:133], v[146:149]
	v_mfma_f32_16x16x32_bf16 v[122:125], v[62:65], v[150:153], v[122:125]
	v_mfma_f32_16x16x32_bf16 v[122:125], v[74:77], v[162:165], v[122:125]
	v_mfma_f32_16x16x32_bf16 v[98:101], v[74:77], v[178:181], v[98:101]
	v_mfma_f32_16x16x32_bf16 v[98:101], v[62:65], v[174:177], v[98:101]
	v_mfma_f32_16x16x32_bf16 v[90:93], v[82:85], v[174:177], v[90:93]
	v_mfma_f32_16x16x32_bf16 v[90:93], v[94:97], v[178:181], v[90:93]
	v_mfma_f32_16x16x32_bf16 v[114:117], v[94:97], v[162:165], v[114:117]
	v_mfma_f32_16x16x32_bf16 v[114:117], v[82:85], v[150:153], v[114:117]
	v_mfma_f32_16x16x32_bf16 v[138:141], v[82:85], v[130:133], v[138:141]
	v_mfma_f32_16x16x32_bf16 v[138:141], v[94:97], v[142:145], v[138:141]
	v_mfma_f32_16x16x32_bf16 v[166:169], v[94:97], v[118:121], v[166:169]
	s_barrier
	v_mfma_f32_16x16x32_bf16 v[166:169], v[82:85], v[106:109], v[166:169]
	s_setprio 0
	s_add_i32 s44, 0, 0x14000
	s_add_i32 s16, s33, s29
	v_add_u32_e32 v2, s44, v200
	v_lshl_add_u64 v[226:227], s[20:21], 0, v[208:209]
	s_mov_b32 m0, s16
	ds_read_b128 v[182:185], v2
	ds_read_b128 v[186:189], v2 offset:1024
	ds_read_b128 v[190:193], v2 offset:2048
	ds_read_b128 v[194:197], v2 offset:3072
	global_load_lds_dwordx4 v[226:227], off
	v_lshl_add_u64 v[228:229], s[20:21], 0, v[204:205]
	s_add_i32 m0, s16, 0x2000
	s_nop 0
	global_load_lds_dwordx4 v[228:229], off
	s_barrier
	s_waitcnt lgkmcnt(0)
	s_setprio 1
	s_waitcnt lgkmcnt(0)
	v_mfma_f32_16x16x32_bf16 v[158:161], v[182:185], v[106:109], v[158:161]
	v_mfma_f32_16x16x32_bf16 v[158:161], v[186:189], v[118:121], v[158:161]
	v_mfma_f32_16x16x32_bf16 v[106:109], v[190:193], v[106:109], v[154:157]
	v_mfma_f32_16x16x32_bf16 v[106:109], v[194:197], v[118:121], v[106:109]
	v_mfma_f32_16x16x32_bf16 v[126:129], v[190:193], v[130:133], v[126:129]
	v_mfma_f32_16x16x32_bf16 v[126:129], v[194:197], v[142:145], v[126:129]
	v_mfma_f32_16x16x32_bf16 v[110:113], v[182:185], v[150:153], v[110:113]
	v_mfma_f32_16x16x32_bf16 v[110:113], v[186:189], v[162:165], v[110:113]
	v_mfma_f32_16x16x32_bf16 v[102:105], v[190:193], v[150:153], v[102:105]
	v_mfma_f32_16x16x32_bf16 v[102:105], v[194:197], v[162:165], v[102:105]
	v_mfma_f32_16x16x32_bf16 v[86:89], v[182:185], v[174:177], v[86:89]
	v_mfma_f32_16x16x32_bf16 v[86:89], v[186:189], v[178:181], v[86:89]
	v_mfma_f32_16x16x32_bf16 v[78:81], v[190:193], v[174:177], v[78:81]
	v_mfma_f32_16x16x32_bf16 v[78:81], v[194:197], v[178:181], v[78:81]
	v_mfma_f32_16x16x32_bf16 v[118:121], v[182:185], v[130:133], v[134:137]
	s_barrier
	v_mfma_f32_16x16x32_bf16 v[118:121], v[186:189], v[142:145], v[118:121]
	s_setprio 0
	s_mov_b32 m0, s30
	v_lshl_add_u64 v[230:231], s[22:23], 0, v[210:211]
	ds_read_b128 v[130:133], v202 offset:16384
	ds_read_b128 v[134:137], v202 offset:17408
	ds_read_b128 v[142:145], v202 offset:18432
	ds_read_b128 v[150:153], v202 offset:19456
	ds_read_b128 v[154:157], v202 offset:20480
	ds_read_b128 v[162:165], v202 offset:21504
	ds_read_b128 v[174:177], v202 offset:22528
	ds_read_b128 v[178:181], v202 offset:23552
	global_load_lds_dwordx4 v[230:231], off
	v_lshl_add_u64 v[232:233], s[22:23], 0, v[206:207]
	s_mov_b32 m0, s31
	s_nop 0
	global_load_lds_dwordx4 v[232:233], off
	s_waitcnt vmcnt(10)
	s_barrier
	s_waitcnt lgkmcnt(0)
	s_setprio 1
	s_waitcnt lgkmcnt(0)
	v_mfma_f32_16x16x32_bf16 v[70:73], v[62:65], v[130:133], v[70:73]
	v_mfma_f32_16x16x32_bf16 v[70:73], v[74:77], v[134:137], v[70:73]
	v_mfma_f32_16x16x32_bf16 v[50:53], v[74:77], v[150:153], v[50:53]
	v_mfma_f32_16x16x32_bf16 v[50:53], v[62:65], v[142:145], v[50:53]
	v_mfma_f32_16x16x32_bf16 v[34:37], v[62:65], v[154:157], v[34:37]
	v_mfma_f32_16x16x32_bf16 v[34:37], v[74:77], v[162:165], v[34:37]
	v_mfma_f32_16x16x32_bf16 v[18:21], v[74:77], v[178:181], v[18:21]
	v_mfma_f32_16x16x32_bf16 v[18:21], v[62:65], v[174:177], v[18:21]
	v_mfma_f32_16x16x32_bf16 v[14:17], v[82:85], v[174:177], v[14:17]
	v_mfma_f32_16x16x32_bf16 v[14:17], v[94:97], v[178:181], v[14:17]
	v_mfma_f32_16x16x32_bf16 v[30:33], v[94:97], v[162:165], v[30:33]
	v_mfma_f32_16x16x32_bf16 v[30:33], v[82:85], v[154:157], v[30:33]
	v_mfma_f32_16x16x32_bf16 v[46:49], v[82:85], v[142:145], v[46:49]
	v_mfma_f32_16x16x32_bf16 v[46:49], v[94:97], v[150:153], v[46:49]
	v_mfma_f32_16x16x32_bf16 v[66:69], v[94:97], v[134:137], v[66:69]
	s_barrier
	v_mfma_f32_16x16x32_bf16 v[66:69], v[82:85], v[130:133], v[66:69]
	s_setprio 0
	s_add_u32 s16, s20, 0xc0000
	s_addc_u32 s17, s21, 0
	s_add_i32 s33, s44, s29
	s_mov_b32 m0, s33
	s_nop 0
	global_load_lds_dwordx4 v208, s[16:17]
	v_lshl_add_u64 v[4:5], s[16:17], 0, v[204:205]
	s_add_i32 m0, s33, 0x2000
	s_nop 0
	global_load_lds_dwordx4 v[4:5], off
	s_add_i32 s33, 0, 0x18000
	v_add_u32_e32 v2, s33, v200
	ds_read_b128 v[62:65], v2
	ds_read_b128 v[74:77], v2 offset:1024
	ds_read_b128 v[82:85], v2 offset:2048
	ds_read_b128 v[94:97], v2 offset:3072
	s_waitcnt vmcnt(6)
	s_barrier
	s_setprio 1
	v_mfma_f32_16x16x32_bf16 v[58:61], v[182:185], v[130:133], v[58:61]
	v_mfma_f32_16x16x32_bf16 v[58:61], v[186:189], v[134:137], v[58:61]
	v_mfma_f32_16x16x32_bf16 v[42:45], v[186:189], v[150:153], v[42:45]
	v_mfma_f32_16x16x32_bf16 v[42:45], v[182:185], v[142:145], v[42:45]
	v_mfma_f32_16x16x32_bf16 v[26:29], v[182:185], v[154:157], v[26:29]
	v_mfma_f32_16x16x32_bf16 v[26:29], v[186:189], v[162:165], v[26:29]
	v_mfma_f32_16x16x32_bf16 v[10:13], v[186:189], v[178:181], v[10:13]
	v_mfma_f32_16x16x32_bf16 v[10:13], v[182:185], v[174:177], v[10:13]
	v_mfma_f32_16x16x32_bf16 v[4:7], v[190:193], v[174:177], v[6:9]
	v_mfma_f32_16x16x32_bf16 v[4:7], v[194:197], v[178:181], v[4:7]
	v_mfma_f32_16x16x32_bf16 v[22:25], v[194:197], v[162:165], v[22:25]
	v_mfma_f32_16x16x32_bf16 v[22:25], v[190:193], v[154:157], v[22:25]
	v_mfma_f32_16x16x32_bf16 v[38:41], v[190:193], v[142:145], v[38:41]
	v_mfma_f32_16x16x32_bf16 v[38:41], v[194:197], v[150:153], v[38:41]
	v_mfma_f32_16x16x32_bf16 v[54:57], v[194:197], v[134:137], v[54:57]
	s_barrier
	v_mfma_f32_16x16x32_bf16 v[54:57], v[190:193], v[130:133], v[54:57]
	s_setprio 0
	s_add_u32 s16, s22, 0xc0000
	s_addc_u32 s17, s23, 0
	s_mov_b32 m0, s34
	v_lshl_add_u64 v[8:9], s[16:17], 0, v[210:211]
	ds_read_b128 v[130:133], v202 offset:32768
	ds_read_b128 v[134:137], v202 offset:33792
	ds_read_b128 v[142:145], v202 offset:34816
	ds_read_b128 v[150:153], v202 offset:35840
	ds_read_b128 v[162:165], v202 offset:36864
	ds_read_b128 v[174:177], v202 offset:37888
	ds_read_b128 v[178:181], v202 offset:38912
	ds_read_b128 v[182:185], v202 offset:39936
	global_load_lds_dwordx4 v[8:9], off
	v_lshl_add_u64 v[8:9], s[16:17], 0, v[206:207]
	s_mov_b32 m0, s35
	s_nop 0
	global_load_lds_dwordx4 v[8:9], off
	s_waitcnt lgkmcnt(8)
	s_barrier
	s_waitcnt lgkmcnt(0)
	s_setprio 1
	s_waitcnt lgkmcnt(0)
	v_mfma_f32_16x16x32_bf16 v[154:157], v[62:65], v[130:133], v[170:173]
	v_mfma_f32_16x16x32_bf16 v[170:173], v[74:77], v[134:137], v[154:157]
	v_mfma_f32_16x16x32_bf16 v[154:157], v[82:85], v[130:133], v[166:169]
	v_mfma_f32_16x16x32_bf16 v[166:169], v[94:97], v[134:137], v[154:157]
	v_mfma_f32_16x16x32_bf16 v[146:149], v[62:65], v[142:145], v[146:149]
	v_mfma_f32_16x16x32_bf16 v[146:149], v[74:77], v[150:153], v[146:149]
	v_mfma_f32_16x16x32_bf16 v[138:141], v[82:85], v[142:145], v[138:141]
	v_mfma_f32_16x16x32_bf16 v[138:141], v[94:97], v[150:153], v[138:141]
	v_mfma_f32_16x16x32_bf16 v[122:125], v[62:65], v[162:165], v[122:125]
	v_mfma_f32_16x16x32_bf16 v[122:125], v[74:77], v[174:177], v[122:125]
	v_mfma_f32_16x16x32_bf16 v[114:117], v[82:85], v[162:165], v[114:117]
	v_mfma_f32_16x16x32_bf16 v[114:117], v[94:97], v[174:177], v[114:117]
	v_mfma_f32_16x16x32_bf16 v[98:101], v[62:65], v[178:181], v[98:101]
	v_mfma_f32_16x16x32_bf16 v[98:101], v[74:77], v[182:185], v[98:101]
	v_mfma_f32_16x16x32_bf16 v[90:93], v[82:85], v[178:181], v[90:93]
	s_barrier
	v_mfma_f32_16x16x32_bf16 v[90:93], v[94:97], v[182:185], v[90:93]
	s_setprio 0
	s_add_i32 s22, 0, 0x1c000
	s_add_i32 s16, s33, s29
	v_add_u32_e32 v2, s22, v200
	v_lshl_add_u64 v[8:9], v[226:227], 0, s[2:3]
	s_mov_b32 m0, s16
	ds_read_b128 v[186:189], v2
	ds_read_b128 v[190:193], v2 offset:1024
	ds_read_b128 v[194:197], v2 offset:2048
	ds_read_b128 v[220:223], v2 offset:3072
	global_load_lds_dwordx4 v[8:9], off
	v_lshl_add_u64 v[8:9], v[228:229], 0, s[2:3]
	s_add_i32 m0, s16, 0x2000
	s_nop 0
	global_load_lds_dwordx4 v[8:9], off
	s_barrier
	s_waitcnt lgkmcnt(0)
	s_setprio 1
	s_waitcnt lgkmcnt(0)
	v_mfma_f32_16x16x32_bf16 v[154:157], v[186:189], v[130:133], v[158:161]
	v_mfma_f32_16x16x32_bf16 v[158:161], v[190:193], v[134:137], v[154:157]
	v_mfma_f32_16x16x32_bf16 v[106:109], v[194:197], v[130:133], v[106:109]
	v_mfma_f32_16x16x32_bf16 v[154:157], v[220:223], v[134:137], v[106:109]
	v_mfma_f32_16x16x32_bf16 v[106:109], v[186:189], v[142:145], v[118:121]
	v_mfma_f32_16x16x32_bf16 v[134:137], v[190:193], v[150:153], v[106:109]
	v_mfma_f32_16x16x32_bf16 v[106:109], v[194:197], v[142:145], v[126:129]
	v_mfma_f32_16x16x32_bf16 v[126:129], v[220:223], v[150:153], v[106:109]
	v_mfma_f32_16x16x32_bf16 v[106:109], v[186:189], v[162:165], v[110:113]
	v_mfma_f32_16x16x32_bf16 v[110:113], v[190:193], v[174:177], v[106:109]
	v_mfma_f32_16x16x32_bf16 v[102:105], v[194:197], v[162:165], v[102:105]
	v_mfma_f32_16x16x32_bf16 v[102:105], v[220:223], v[174:177], v[102:105]
	v_mfma_f32_16x16x32_bf16 v[86:89], v[186:189], v[178:181], v[86:89]
	v_mfma_f32_16x16x32_bf16 v[86:89], v[190:193], v[182:185], v[86:89]
	v_mfma_f32_16x16x32_bf16 v[78:81], v[194:197], v[178:181], v[78:81]
	s_barrier
	v_mfma_f32_16x16x32_bf16 v[78:81], v[220:223], v[182:185], v[78:81]
	s_setprio 0
	s_mov_b32 m0, s36
	v_lshl_add_u64 v[8:9], v[230:231], 0, s[2:3]
	ds_read_b128 v[106:109], v202 offset:49152
	ds_read_b128 v[118:121], v202 offset:50176
	ds_read_b128 v[130:133], v202 offset:51200
	ds_read_b128 v[142:145], v202 offset:52224
	ds_read_b128 v[150:153], v202 offset:53248
	ds_read_b128 v[162:165], v202 offset:54272
	ds_read_b128 v[174:177], v202 offset:55296
	ds_read_b128 v[178:181], v202 offset:56320
	global_load_lds_dwordx4 v[8:9], off
	v_lshl_add_u64 v[8:9], v[232:233], 0, s[2:3]
	s_mov_b32 m0, s37
	s_nop 0
	global_load_lds_dwordx4 v[8:9], off
	s_barrier
	s_waitcnt lgkmcnt(0)
	s_setprio 1
	s_waitcnt lgkmcnt(0)
	v_mfma_f32_16x16x32_bf16 v[70:73], v[62:65], v[106:109], v[70:73]
	v_mfma_f32_16x16x32_bf16 v[70:73], v[74:77], v[118:121], v[70:73]
	v_mfma_f32_16x16x32_bf16 v[50:53], v[74:77], v[142:145], v[50:53]
	v_mfma_f32_16x16x32_bf16 v[50:53], v[62:65], v[130:133], v[50:53]
	v_mfma_f32_16x16x32_bf16 v[34:37], v[62:65], v[150:153], v[34:37]
	v_mfma_f32_16x16x32_bf16 v[34:37], v[74:77], v[162:165], v[34:37]
	v_mfma_f32_16x16x32_bf16 v[18:21], v[74:77], v[178:181], v[18:21]
	v_mfma_f32_16x16x32_bf16 v[18:21], v[62:65], v[174:177], v[18:21]
	v_mfma_f32_16x16x32_bf16 v[14:17], v[82:85], v[174:177], v[14:17]
	v_mfma_f32_16x16x32_bf16 v[14:17], v[94:97], v[178:181], v[14:17]
	v_mfma_f32_16x16x32_bf16 v[30:33], v[94:97], v[162:165], v[30:33]
	v_mfma_f32_16x16x32_bf16 v[30:33], v[82:85], v[150:153], v[30:33]
	v_mfma_f32_16x16x32_bf16 v[46:49], v[82:85], v[130:133], v[46:49]
	v_mfma_f32_16x16x32_bf16 v[46:49], v[94:97], v[142:145], v[46:49]
	v_mfma_f32_16x16x32_bf16 v[66:69], v[94:97], v[118:121], v[66:69]
	s_barrier
	v_mfma_f32_16x16x32_bf16 v[66:69], v[82:85], v[106:109], v[66:69]
	s_setprio 0
	s_add_u32 s16, s20, 0xc0080
	s_addc_u32 s17, s21, 0
	s_add_i32 s20, s22, s29
	v_lshl_add_u64 v[8:9], s[16:17], 0, v[208:209]
	s_mov_b32 m0, s20
	s_nop 0
	global_load_lds_dwordx4 v[8:9], off
	v_lshl_add_u64 v[8:9], s[16:17], 0, v[204:205]
	s_add_i32 m0, s20, 0x2000
	s_nop 0
	global_load_lds_dwordx4 v[8:9], off
	s_waitcnt vmcnt(6)
	s_barrier
	s_setprio 1
	v_mfma_f32_16x16x32_bf16 v[58:61], v[186:189], v[106:109], v[58:61]
	v_mfma_f32_16x16x32_bf16 v[58:61], v[190:193], v[118:121], v[58:61]
	v_mfma_f32_16x16x32_bf16 v[54:57], v[194:197], v[106:109], v[54:57]
	v_mfma_f32_16x16x32_bf16 v[54:57], v[220:223], v[118:121], v[54:57]
	v_mfma_f32_16x16x32_bf16 v[42:45], v[186:189], v[130:133], v[42:45]
	v_mfma_f32_16x16x32_bf16 v[42:45], v[190:193], v[142:145], v[42:45]
	v_mfma_f32_16x16x32_bf16 v[38:41], v[194:197], v[130:133], v[38:41]
	v_mfma_f32_16x16x32_bf16 v[38:41], v[220:223], v[142:145], v[38:41]
	v_mfma_f32_16x16x32_bf16 v[26:29], v[186:189], v[150:153], v[26:29]
	v_mfma_f32_16x16x32_bf16 v[26:29], v[190:193], v[162:165], v[26:29]
	v_mfma_f32_16x16x32_bf16 v[22:25], v[194:197], v[150:153], v[22:25]
	v_mfma_f32_16x16x32_bf16 v[22:25], v[220:223], v[162:165], v[22:25]
	v_mfma_f32_16x16x32_bf16 v[8:11], v[186:189], v[174:177], v[10:13]
	v_mfma_f32_16x16x32_bf16 v[10:13], v[190:193], v[178:181], v[8:11]
	v_mfma_f32_16x16x32_bf16 v[4:7], v[194:197], v[174:177], v[4:7]
	s_barrier
	v_mfma_f32_16x16x32_bf16 v[6:9], v[220:223], v[178:181], v[4:7]
	s_setprio 0
	s_add_u32 s14, s14, 0x200
	s_addc_u32 s15, s15, 0
	s_add_u32 s41, s41, 0x100
	s_addc_u32 s42, s42, 0
	s_cmp_gt_u32 s43, 45
	s_cbranch_scc1 .LBB0_806
	s_mov_b64 s[16:17], s[18:19]
	s_branch .LBB0_814

.LBB0_878:
	s_add_u32 s22, s20, 0xfff80080
	s_addc_u32 s23, s21, -1
	s_add_i32 s49, 0, 0x10000
	s_waitcnt vmcnt(0)
	v_add_u32_e32 v144, s49, v188
	ds_read_b128 v[132:135], v144
	ds_read_b128 v[136:139], v144 offset:1024
	ds_read_b128 v[140:143], v144 offset:2048
	ds_read_b128 v[144:147], v144 offset:3072
	s_cmp_eq_u32 s48, 28
	s_cselect_b32 s25, s15, s23
	s_cselect_b32 s24, s44, s22
	s_cselect_b32 s23, s13, s47
	s_cselect_b32 s22, s45, s46
	s_add_i32 m0, s34, 0xc000
	ds_read_b128 v[148:151], v190
	ds_read_b128 v[152:155], v190 offset:1024
	ds_read_b128 v[156:159], v190 offset:2048
	ds_read_b128 v[160:163], v190 offset:3072
	ds_read_b128 v[174:177], v190 offset:4096
	ds_read_b128 v[178:181], v190 offset:5120
	ds_read_b128 v[182:185], v190 offset:6144
	ds_read_b128 v[192:195], v190 offset:7168
	global_load_lds_dwordx4 v170, s[20:21]
	s_add_i32 m0, s34, 0xe000
	s_nop 0
	global_load_lds_dwordx4 v172, s[20:21]
	s_waitcnt lgkmcnt(8)
	s_barrier
	s_waitcnt lgkmcnt(0)
	s_setprio 1
	s_waitcnt lgkmcnt(0)
	v_mfma_f32_16x16x32_bf16 v[128:131], v[132:135], v[148:151], v[128:131]
	v_mfma_f32_16x16x32_bf16 v[128:131], v[136:139], v[152:155], v[128:131]
	v_mfma_f32_16x16x32_bf16 v[120:123], v[136:139], v[160:163], v[120:123]
	v_mfma_f32_16x16x32_bf16 v[120:123], v[132:135], v[156:159], v[120:123]
	v_mfma_f32_16x16x32_bf16 v[96:99], v[132:135], v[174:177], v[96:99]
	v_mfma_f32_16x16x32_bf16 v[96:99], v[136:139], v[178:181], v[96:99]
	v_mfma_f32_16x16x32_bf16 v[88:91], v[136:139], v[192:195], v[88:91]
	v_mfma_f32_16x16x32_bf16 v[88:91], v[132:135], v[182:185], v[88:91]
	v_mfma_f32_16x16x32_bf16 v[84:87], v[140:143], v[182:185], v[84:87]
	v_mfma_f32_16x16x32_bf16 v[84:87], v[144:147], v[192:195], v[84:87]
	v_mfma_f32_16x16x32_bf16 v[92:95], v[144:147], v[178:181], v[92:95]
	v_mfma_f32_16x16x32_bf16 v[92:95], v[140:143], v[174:177], v[92:95]
	v_mfma_f32_16x16x32_bf16 v[116:119], v[140:143], v[156:159], v[116:119]
	v_mfma_f32_16x16x32_bf16 v[116:119], v[144:147], v[160:163], v[116:119]
	v_mfma_f32_16x16x32_bf16 v[124:127], v[144:147], v[152:155], v[124:127]
	s_barrier
	v_mfma_f32_16x16x32_bf16 v[124:127], v[140:143], v[148:151], v[124:127]
	s_setprio 0
	s_add_i32 s52, 0, 0x14000
	v_add_u32_e32 v186, s52, v188
	s_add_i32 s49, s49, s31
	ds_read_b128 v[200:203], v186
	ds_read_b128 v[204:207], v186 offset:1024
	ds_read_b128 v[208:211], v186 offset:2048
	ds_read_b128 v[212:215], v186 offset:3072
	v_lshl_add_u64 v[186:187], s[22:23], 0, v[2:3]
	s_mov_b32 m0, s49
	v_lshl_add_u64 v[196:197], s[22:23], 0, v[164:165]
	global_load_lds_dwordx4 v[186:187], off
	s_add_i32 m0, s49, 0x2000
	s_nop 0
	global_load_lds_dwordx4 v[196:197], off
	s_barrier
	s_waitcnt lgkmcnt(0)
	s_setprio 1
	s_waitcnt lgkmcnt(0)
	v_mfma_f32_16x16x32_bf16 v[112:115], v[200:203], v[148:151], v[112:115]
	v_mfma_f32_16x16x32_bf16 v[112:115], v[204:207], v[152:155], v[112:115]
	v_mfma_f32_16x16x32_bf16 v[104:107], v[204:207], v[160:163], v[104:107]
	v_mfma_f32_16x16x32_bf16 v[104:107], v[200:203], v[156:159], v[104:107]
	v_mfma_f32_16x16x32_bf16 v[80:83], v[200:203], v[174:177], v[80:83]
	v_mfma_f32_16x16x32_bf16 v[80:83], v[204:207], v[178:181], v[80:83]
	v_mfma_f32_16x16x32_bf16 v[72:75], v[204:207], v[192:195], v[72:75]
	v_mfma_f32_16x16x32_bf16 v[72:75], v[200:203], v[182:185], v[72:75]
	v_mfma_f32_16x16x32_bf16 v[68:71], v[208:211], v[182:185], v[68:71]
	v_mfma_f32_16x16x32_bf16 v[68:71], v[212:215], v[192:195], v[68:71]
	v_mfma_f32_16x16x32_bf16 v[76:79], v[212:215], v[178:181], v[76:79]
	v_mfma_f32_16x16x32_bf16 v[76:79], v[208:211], v[174:177], v[76:79]
	v_mfma_f32_16x16x32_bf16 v[100:103], v[208:211], v[156:159], v[100:103]
	v_mfma_f32_16x16x32_bf16 v[100:103], v[212:215], v[160:163], v[100:103]
	v_mfma_f32_16x16x32_bf16 v[108:111], v[212:215], v[152:155], v[108:111]
	s_barrier
	v_mfma_f32_16x16x32_bf16 v[108:111], v[208:211], v[148:151], v[108:111]
	s_setprio 0
	s_mov_b32 m0, s34
	v_lshl_add_u64 v[216:217], s[24:25], 0, v[168:169]
	ds_read_b128 v[148:151], v190 offset:16384
	ds_read_b128 v[152:155], v190 offset:17408
	ds_read_b128 v[156:159], v190 offset:18432
	ds_read_b128 v[160:163], v190 offset:19456
	ds_read_b128 v[174:177], v190 offset:20480
	ds_read_b128 v[178:181], v190 offset:21504
	ds_read_b128 v[182:185], v190 offset:22528
	ds_read_b128 v[192:195], v190 offset:23552
	global_load_lds_dwordx4 v[216:217], off
	v_lshl_add_u64 v[218:219], s[24:25], 0, v[166:167]
	s_mov_b32 m0, s35
	s_nop 0
	global_load_lds_dwordx4 v[218:219], off
	s_waitcnt vmcnt(10)
	s_barrier
	s_waitcnt lgkmcnt(0)
	s_setprio 1
	s_waitcnt lgkmcnt(0)
	v_mfma_f32_16x16x32_bf16 v[64:67], v[132:135], v[148:151], v[64:67]
	v_mfma_f32_16x16x32_bf16 v[64:67], v[136:139], v[152:155], v[64:67]
	v_mfma_f32_16x16x32_bf16 v[56:59], v[136:139], v[160:163], v[56:59]
	v_mfma_f32_16x16x32_bf16 v[56:59], v[132:135], v[156:159], v[56:59]
	v_mfma_f32_16x16x32_bf16 v[32:35], v[132:135], v[174:177], v[32:35]
	v_mfma_f32_16x16x32_bf16 v[32:35], v[136:139], v[178:181], v[32:35]
	v_mfma_f32_16x16x32_bf16 v[24:27], v[136:139], v[192:195], v[24:27]
	v_mfma_f32_16x16x32_bf16 v[24:27], v[132:135], v[182:185], v[24:27]
	v_mfma_f32_16x16x32_bf16 v[20:23], v[140:143], v[182:185], v[20:23]
	v_mfma_f32_16x16x32_bf16 v[20:23], v[144:147], v[192:195], v[20:23]
	v_mfma_f32_16x16x32_bf16 v[28:31], v[144:147], v[178:181], v[28:31]
	v_mfma_f32_16x16x32_bf16 v[28:31], v[140:143], v[174:177], v[28:31]
	v_mfma_f32_16x16x32_bf16 v[52:55], v[140:143], v[156:159], v[52:55]
	v_mfma_f32_16x16x32_bf16 v[52:55], v[144:147], v[160:163], v[52:55]
	v_mfma_f32_16x16x32_bf16 v[60:63], v[144:147], v[152:155], v[60:63]
	s_barrier
	v_mfma_f32_16x16x32_bf16 v[60:63], v[140:143], v[148:151], v[60:63]
	s_setprio 0
	s_add_u32 s50, s22, 0x80000
	s_addc_u32 s51, s23, 0
	s_add_i32 s49, s52, s31
	v_lshl_add_u64 v[132:133], s[50:51], 0, v[2:3]
	s_mov_b32 m0, s49
	s_nop 0
	global_load_lds_dwordx4 v[132:133], off
	v_lshl_add_u64 v[132:133], s[50:51], 0, v[164:165]
	s_add_i32 m0, s49, 0x2000
	s_nop 0
	global_load_lds_dwordx4 v[132:133], off
	s_add_i32 s49, 0, 0x18000
	v_add_u32_e32 v144, s49, v188
	ds_read_b128 v[132:135], v144
	ds_read_b128 v[136:139], v144 offset:1024
	ds_read_b128 v[140:143], v144 offset:2048
	ds_read_b128 v[144:147], v144 offset:3072
	s_waitcnt vmcnt(6)
	s_barrier
	s_setprio 1
	v_mfma_f32_16x16x32_bf16 v[48:51], v[200:203], v[148:151], v[48:51]
	v_mfma_f32_16x16x32_bf16 v[48:51], v[204:207], v[152:155], v[48:51]
	v_mfma_f32_16x16x32_bf16 v[40:43], v[204:207], v[160:163], v[40:43]
	v_mfma_f32_16x16x32_bf16 v[40:43], v[200:203], v[156:159], v[40:43]
	v_mfma_f32_16x16x32_bf16 v[16:19], v[200:203], v[174:177], v[16:19]
	v_mfma_f32_16x16x32_bf16 v[16:19], v[204:207], v[178:181], v[16:19]
	v_mfma_f32_16x16x32_bf16 v[8:11], v[204:207], v[192:195], v[8:11]
	v_mfma_f32_16x16x32_bf16 v[8:11], v[200:203], v[182:185], v[8:11]
	v_mfma_f32_16x16x32_bf16 v[4:7], v[208:211], v[182:185], v[4:7]
	v_mfma_f32_16x16x32_bf16 v[4:7], v[212:215], v[192:195], v[4:7]
	v_mfma_f32_16x16x32_bf16 v[12:15], v[212:215], v[178:181], v[12:15]
	v_mfma_f32_16x16x32_bf16 v[12:15], v[208:211], v[174:177], v[12:15]
	v_mfma_f32_16x16x32_bf16 v[36:39], v[208:211], v[156:159], v[36:39]
	v_mfma_f32_16x16x32_bf16 v[36:39], v[212:215], v[160:163], v[36:39]
	v_mfma_f32_16x16x32_bf16 v[44:47], v[212:215], v[152:155], v[44:47]
	s_barrier
	v_mfma_f32_16x16x32_bf16 v[44:47], v[208:211], v[148:151], v[44:47]
	s_setprio 0
	s_add_u32 s24, s24, 0x80000
	s_addc_u32 s25, s25, 0
	s_mov_b32 m0, s36
	v_lshl_add_u64 v[200:201], s[24:25], 0, v[168:169]
	ds_read_b128 v[148:151], v190 offset:32768
	ds_read_b128 v[152:155], v190 offset:33792
	ds_read_b128 v[156:159], v190 offset:34816
	ds_read_b128 v[160:163], v190 offset:35840
	ds_read_b128 v[174:177], v190 offset:36864
	ds_read_b128 v[178:181], v190 offset:37888
	ds_read_b128 v[182:185], v190 offset:38912
	ds_read_b128 v[192:195], v190 offset:39936
	global_load_lds_dwordx4 v[200:201], off
	v_lshl_add_u64 v[200:201], s[24:25], 0, v[166:167]
	s_mov_b32 m0, s37
	s_nop 0
	global_load_lds_dwordx4 v[200:201], off
	s_waitcnt lgkmcnt(8)
	s_barrier
	s_waitcnt lgkmcnt(0)
	s_setprio 1
	s_waitcnt lgkmcnt(0)
	v_mfma_f32_16x16x32_bf16 v[128:131], v[132:135], v[148:151], v[128:131]
	v_mfma_f32_16x16x32_bf16 v[128:131], v[136:139], v[152:155], v[128:131]
	v_mfma_f32_16x16x32_bf16 v[120:123], v[136:139], v[160:163], v[120:123]
	v_mfma_f32_16x16x32_bf16 v[120:123], v[132:135], v[156:159], v[120:123]
	v_mfma_f32_16x16x32_bf16 v[96:99], v[132:135], v[174:177], v[96:99]
	v_mfma_f32_16x16x32_bf16 v[96:99], v[136:139], v[178:181], v[96:99]
	v_mfma_f32_16x16x32_bf16 v[88:91], v[136:139], v[192:195], v[88:91]
	v_mfma_f32_16x16x32_bf16 v[88:91], v[132:135], v[182:185], v[88:91]
	v_mfma_f32_16x16x32_bf16 v[84:87], v[140:143], v[182:185], v[84:87]
	v_mfma_f32_16x16x32_bf16 v[84:87], v[144:147], v[192:195], v[84:87]
	v_mfma_f32_16x16x32_bf16 v[92:95], v[144:147], v[178:181], v[92:95]
	v_mfma_f32_16x16x32_bf16 v[92:95], v[140:143], v[174:177], v[92:95]
	v_mfma_f32_16x16x32_bf16 v[116:119], v[140:143], v[156:159], v[116:119]
	v_mfma_f32_16x16x32_bf16 v[116:119], v[144:147], v[160:163], v[116:119]
	v_mfma_f32_16x16x32_bf16 v[124:127], v[144:147], v[152:155], v[124:127]
	s_barrier
	v_mfma_f32_16x16x32_bf16 v[124:127], v[140:143], v[148:151], v[124:127]
	s_setprio 0
	s_add_i32 s24, 0, 0x1c000
	s_add_i32 s25, s49, s31
	v_add_u32_e32 v191, s24, v188
	v_lshl_add_u64 v[186:187], v[186:187], 0, s[2:3]
	s_mov_b32 m0, s25
	ds_read_b128 v[200:203], v191
	ds_read_b128 v[204:207], v191 offset:1024
	ds_read_b128 v[208:211], v191 offset:2048
	ds_read_b128 v[212:215], v191 offset:3072
	global_load_lds_dwordx4 v[186:187], off
	v_lshl_add_u64 v[186:187], v[196:197], 0, s[2:3]
	s_add_i32 m0, s25, 0x2000
	s_nop 0
	global_load_lds_dwordx4 v[186:187], off
	s_barrier
	s_waitcnt lgkmcnt(0)
	s_setprio 1
	s_waitcnt lgkmcnt(0)
	v_mfma_f32_16x16x32_bf16 v[112:115], v[200:203], v[148:151], v[112:115]
	v_mfma_f32_16x16x32_bf16 v[112:115], v[204:207], v[152:155], v[112:115]
	v_mfma_f32_16x16x32_bf16 v[104:107], v[204:207], v[160:163], v[104:107]
	v_mfma_f32_16x16x32_bf16 v[104:107], v[200:203], v[156:159], v[104:107]
	v_mfma_f32_16x16x32_bf16 v[80:83], v[200:203], v[174:177], v[80:83]
	v_mfma_f32_16x16x32_bf16 v[80:83], v[204:207], v[178:181], v[80:83]
	v_mfma_f32_16x16x32_bf16 v[72:75], v[204:207], v[192:195], v[72:75]
	v_mfma_f32_16x16x32_bf16 v[72:75], v[200:203], v[182:185], v[72:75]
	v_mfma_f32_16x16x32_bf16 v[68:71], v[208:211], v[182:185], v[68:71]
	v_mfma_f32_16x16x32_bf16 v[68:71], v[212:215], v[192:195], v[68:71]
	v_mfma_f32_16x16x32_bf16 v[76:79], v[212:215], v[178:181], v[76:79]
	v_mfma_f32_16x16x32_bf16 v[76:79], v[208:211], v[174:177], v[76:79]
	v_mfma_f32_16x16x32_bf16 v[100:103], v[208:211], v[156:159], v[100:103]
	v_mfma_f32_16x16x32_bf16 v[100:103], v[212:215], v[160:163], v[100:103]
	v_mfma_f32_16x16x32_bf16 v[108:111], v[212:215], v[152:155], v[108:111]
	s_barrier
	v_mfma_f32_16x16x32_bf16 v[108:111], v[208:211], v[148:151], v[108:111]
	s_setprio 0
	s_mov_b32 m0, s41
	v_lshl_add_u64 v[186:187], v[216:217], 0, s[2:3]
	ds_read_b128 v[148:151], v190 offset:49152
	ds_read_b128 v[152:155], v190 offset:50176
	ds_read_b128 v[156:159], v190 offset:51200
	ds_read_b128 v[160:163], v190 offset:52224
	ds_read_b128 v[174:177], v190 offset:53248
	ds_read_b128 v[178:181], v190 offset:54272
	ds_read_b128 v[182:185], v190 offset:55296
	ds_read_b128 v[192:195], v190 offset:56320
	global_load_lds_dwordx4 v[186:187], off
	v_lshl_add_u64 v[186:187], v[218:219], 0, s[2:3]
	s_mov_b32 m0, s42
	s_nop 0
	global_load_lds_dwordx4 v[186:187], off
	s_barrier
	s_waitcnt lgkmcnt(0)
	s_setprio 1
	s_waitcnt lgkmcnt(0)
	v_mfma_f32_16x16x32_bf16 v[64:67], v[132:135], v[148:151], v[64:67]
	v_mfma_f32_16x16x32_bf16 v[64:67], v[136:139], v[152:155], v[64:67]
	v_mfma_f32_16x16x32_bf16 v[56:59], v[136:139], v[160:163], v[56:59]
	v_mfma_f32_16x16x32_bf16 v[56:59], v[132:135], v[156:159], v[56:59]
	v_mfma_f32_16x16x32_bf16 v[32:35], v[132:135], v[174:177], v[32:35]
	v_mfma_f32_16x16x32_bf16 v[32:35], v[136:139], v[178:181], v[32:35]
	v_mfma_f32_16x16x32_bf16 v[24:27], v[136:139], v[192:195], v[24:27]
	v_mfma_f32_16x16x32_bf16 v[24:27], v[132:135], v[182:185], v[24:27]
	v_mfma_f32_16x16x32_bf16 v[20:23], v[140:143], v[182:185], v[20:23]
	v_mfma_f32_16x16x32_bf16 v[20:23], v[144:147], v[192:195], v[20:23]
	v_mfma_f32_16x16x32_bf16 v[28:31], v[144:147], v[178:181], v[28:31]
	v_mfma_f32_16x16x32_bf16 v[28:31], v[140:143], v[174:177], v[28:31]
	v_mfma_f32_16x16x32_bf16 v[52:55], v[140:143], v[156:159], v[52:55]
	v_mfma_f32_16x16x32_bf16 v[52:55], v[144:147], v[160:163], v[52:55]
	v_mfma_f32_16x16x32_bf16 v[60:63], v[144:147], v[152:155], v[60:63]
	s_barrier
	v_mfma_f32_16x16x32_bf16 v[60:63], v[140:143], v[148:151], v[60:63]
	s_setprio 0
	s_add_u32 s22, s22, 0x80080
	s_addc_u32 s23, s23, 0
	s_add_i32 s24, s24, s31
	v_lshl_add_u64 v[132:133], s[22:23], 0, v[2:3]
	s_mov_b32 m0, s24
	s_nop 0
	global_load_lds_dwordx4 v[132:133], off
	v_lshl_add_u64 v[132:133], s[22:23], 0, v[164:165]
	s_add_i32 m0, s24, 0x2000
	s_nop 0
	global_load_lds_dwordx4 v[132:133], off
	s_waitcnt vmcnt(6)
	s_barrier
	s_setprio 1
	v_mfma_f32_16x16x32_bf16 v[48:51], v[200:203], v[148:151], v[48:51]
	v_mfma_f32_16x16x32_bf16 v[48:51], v[204:207], v[152:155], v[48:51]
	v_mfma_f32_16x16x32_bf16 v[40:43], v[204:207], v[160:163], v[40:43]
	v_mfma_f32_16x16x32_bf16 v[40:43], v[200:203], v[156:159], v[40:43]
	v_mfma_f32_16x16x32_bf16 v[16:19], v[200:203], v[174:177], v[16:19]
	v_mfma_f32_16x16x32_bf16 v[16:19], v[204:207], v[178:181], v[16:19]
	v_mfma_f32_16x16x32_bf16 v[8:11], v[204:207], v[192:195], v[8:11]
	v_mfma_f32_16x16x32_bf16 v[8:11], v[200:203], v[182:185], v[8:11]
	v_mfma_f32_16x16x32_bf16 v[4:7], v[208:211], v[182:185], v[4:7]
	v_mfma_f32_16x16x32_bf16 v[4:7], v[212:215], v[192:195], v[4:7]
	v_mfma_f32_16x16x32_bf16 v[12:15], v[212:215], v[178:181], v[12:15]
	v_mfma_f32_16x16x32_bf16 v[12:15], v[208:211], v[174:177], v[12:15]
	v_mfma_f32_16x16x32_bf16 v[36:39], v[208:211], v[156:159], v[36:39]
	v_mfma_f32_16x16x32_bf16 v[36:39], v[212:215], v[160:163], v[36:39]
	v_mfma_f32_16x16x32_bf16 v[44:47], v[212:215], v[152:155], v[44:47]
	s_barrier
	v_mfma_f32_16x16x32_bf16 v[44:47], v[208:211], v[148:151], v[44:47]
	s_setprio 0
	s_add_i32 s48, s48, 2
	s_add_u32 s20, s20, 0x100
	s_addc_u32 s21, s21, 0
	s_add_u32 s46, s46, 0x100
	s_addc_u32 s47, s47, 0
	s_cmp_gt_u32 s48, 29
	s_cbranch_scc0 .LBB0_878
	s_cmp_lt_i32 s43, 32
	s_mov_b64 s[20:21], 0
	s_cbranch_scc1 .LBB0_881
	s_sub_i32 s13, s43, 32
	s_lshr_b32 s13, s13, 4
	s_add_i32 s13, s13, 1
	s_mul_hi_u32 s21, s13, 0x3000
	s_mul_i32 s20, s13, 0x3000

.LBB0_1002:
	s_add_u32 s28, s26, 0x100
	s_addc_u32 s29, s27, 0
	s_add_i32 s58, 0, 0x10000
	v_add_u32_e32 v56, s58, v1
	ds_read_b128 v[44:47], v56
	ds_read_b128 v[48:51], v56 offset:1024
	ds_read_b128 v[52:55], v56 offset:2048
	ds_read_b128 v[56:59], v56 offset:3072
	s_cmp_eq_u32 s57, 28
	s_cselect_b32 s35, s21, s29
	s_cselect_b32 s34, s53, s28
	s_cselect_b32 s31, s19, s56
	s_cselect_b32 s30, s54, s55
	v_lshl_add_u64 v[190:191], s[26:27], 0, v[178:179]
	s_add_i32 m0, s42, 0xc000
	ds_read_b128 v[68:71], v200
	ds_read_b128 v[72:75], v200 offset:1024
	ds_read_b128 v[76:79], v200 offset:2048
	ds_read_b128 v[80:83], v200 offset:3072
	ds_read_b128 v[164:167], v200 offset:4096
	ds_read_b128 v[168:171], v200 offset:5120
	ds_read_b128 v[182:185], v200 offset:6144
	ds_read_b128 v[186:189], v200 offset:7168
	global_load_lds_dwordx4 v[190:191], off
	v_lshl_add_u64 v[190:191], s[26:27], 0, v[180:181]
	s_add_i32 m0, s42, 0xe000
	s_nop 0
	global_load_lds_dwordx4 v[190:191], off
	s_waitcnt lgkmcnt(8)
	s_barrier
	s_waitcnt lgkmcnt(0)
	s_setprio 1
	s_waitcnt lgkmcnt(0)
	v_mfma_f32_16x16x32_bf16 v[160:163], v[44:47], v[68:71], v[160:163]
	v_mfma_f32_16x16x32_bf16 v[160:163], v[48:51], v[72:75], v[160:163]
	v_mfma_f32_16x16x32_bf16 v[148:151], v[48:51], v[80:83], v[148:151]
	v_mfma_f32_16x16x32_bf16 v[148:151], v[44:47], v[76:79], v[148:151]
	v_mfma_f32_16x16x32_bf16 v[132:135], v[44:47], v[164:167], v[132:135]
	v_mfma_f32_16x16x32_bf16 v[132:135], v[48:51], v[168:171], v[132:135]
	v_mfma_f32_16x16x32_bf16 v[116:119], v[48:51], v[186:189], v[116:119]
	v_mfma_f32_16x16x32_bf16 v[116:119], v[44:47], v[182:185], v[116:119]
	v_mfma_f32_16x16x32_bf16 v[108:111], v[52:55], v[182:185], v[108:111]
	v_mfma_f32_16x16x32_bf16 v[108:111], v[56:59], v[186:189], v[108:111]
	v_mfma_f32_16x16x32_bf16 v[124:127], v[56:59], v[168:171], v[124:127]
	v_mfma_f32_16x16x32_bf16 v[124:127], v[52:55], v[164:167], v[124:127]
	v_mfma_f32_16x16x32_bf16 v[140:143], v[52:55], v[76:79], v[140:143]
	v_mfma_f32_16x16x32_bf16 v[140:143], v[56:59], v[80:83], v[140:143]
	v_mfma_f32_16x16x32_bf16 v[156:159], v[56:59], v[72:75], v[156:159]
	s_barrier
	v_mfma_f32_16x16x32_bf16 v[156:159], v[52:55], v[68:71], v[156:159]
	s_setprio 0
	s_add_i32 s59, 0, 0x14000
	v_add_u32_e32 v194, s59, v1
	s_add_i32 s26, s58, s41
	ds_read_b128 v[190:193], v194
	ds_read_b128 v[202:205], v194 offset:1024
	ds_read_b128 v[206:209], v194 offset:2048
	ds_read_b128 v[210:213], v194 offset:3072
	v_lshl_add_u64 v[194:195], s[30:31], 0, v[2:3]
	s_mov_b32 m0, s26
	v_lshl_add_u64 v[222:223], s[30:31], 0, v[172:173]
	global_load_lds_dwordx4 v[194:195], off
	s_add_i32 m0, s26, 0x2000
	s_nop 0
	global_load_lds_dwordx4 v[222:223], off
	s_barrier
	s_waitcnt lgkmcnt(0)
	s_setprio 1
	s_waitcnt lgkmcnt(0)
	v_mfma_f32_16x16x32_bf16 v[152:155], v[190:193], v[68:71], v[152:155]
	v_mfma_f32_16x16x32_bf16 v[152:155], v[202:205], v[72:75], v[152:155]
	v_mfma_f32_16x16x32_bf16 v[68:71], v[206:209], v[68:71], v[144:147]
	v_mfma_f32_16x16x32_bf16 v[68:71], v[210:213], v[72:75], v[68:71]
	v_mfma_f32_16x16x32_bf16 v[72:75], v[190:193], v[76:79], v[136:139]
	v_mfma_f32_16x16x32_bf16 v[72:75], v[202:205], v[80:83], v[72:75]
	v_mfma_f32_16x16x32_bf16 v[76:79], v[206:209], v[76:79], v[128:131]
	v_mfma_f32_16x16x32_bf16 v[76:79], v[210:213], v[80:83], v[76:79]
	v_mfma_f32_16x16x32_bf16 v[112:115], v[206:209], v[164:167], v[112:115]
	v_mfma_f32_16x16x32_bf16 v[112:115], v[210:213], v[168:171], v[112:115]
	v_mfma_f32_16x16x32_bf16 v[104:107], v[190:193], v[182:185], v[104:107]
	v_mfma_f32_16x16x32_bf16 v[104:107], v[202:205], v[186:189], v[104:107]
	v_mfma_f32_16x16x32_bf16 v[96:99], v[206:209], v[182:185], v[96:99]
	v_mfma_f32_16x16x32_bf16 v[96:99], v[210:213], v[186:189], v[96:99]
	v_mfma_f32_16x16x32_bf16 v[80:83], v[190:193], v[164:167], v[120:123]
	s_barrier
	v_mfma_f32_16x16x32_bf16 v[80:83], v[202:205], v[168:171], v[80:83]
	s_setprio 0
	s_mov_b32 m0, s42
	v_lshl_add_u64 v[224:225], s[34:35], 0, v[176:177]
	ds_read_b128 v[120:123], v200 offset:16384
	ds_read_b128 v[128:131], v200 offset:17408
	ds_read_b128 v[136:139], v200 offset:18432
	ds_read_b128 v[144:147], v200 offset:19456
	ds_read_b128 v[164:167], v200 offset:20480
	ds_read_b128 v[168:171], v200 offset:21504
	ds_read_b128 v[182:185], v200 offset:22528
	ds_read_b128 v[186:189], v200 offset:23552
	global_load_lds_dwordx4 v[224:225], off
	v_lshl_add_u64 v[226:227], s[34:35], 0, v[174:175]
	s_mov_b32 m0, s43
	s_nop 0
	global_load_lds_dwordx4 v[226:227], off
	s_waitcnt vmcnt(10)
	s_barrier
	s_waitcnt lgkmcnt(0)
	s_setprio 1
	s_waitcnt lgkmcnt(0)
	v_mfma_f32_16x16x32_bf16 v[100:103], v[44:47], v[120:123], v[100:103]
	v_mfma_f32_16x16x32_bf16 v[100:103], v[48:51], v[128:131], v[100:103]
	v_mfma_f32_16x16x32_bf16 v[84:87], v[48:51], v[144:147], v[84:87]
	v_mfma_f32_16x16x32_bf16 v[84:87], v[44:47], v[136:139], v[84:87]
	v_mfma_f32_16x16x32_bf16 v[36:39], v[44:47], v[164:167], v[36:39]
	v_mfma_f32_16x16x32_bf16 v[36:39], v[48:51], v[168:171], v[36:39]
	v_mfma_f32_16x16x32_bf16 v[16:19], v[48:51], v[186:189], v[16:19]
	v_mfma_f32_16x16x32_bf16 v[16:19], v[44:47], v[182:185], v[16:19]
	v_mfma_f32_16x16x32_bf16 v[12:15], v[52:55], v[182:185], v[12:15]
	v_mfma_f32_16x16x32_bf16 v[12:15], v[56:59], v[186:189], v[12:15]
	v_mfma_f32_16x16x32_bf16 v[28:31], v[56:59], v[168:171], v[28:31]
	v_mfma_f32_16x16x32_bf16 v[28:31], v[52:55], v[164:167], v[28:31]
	v_mfma_f32_16x16x32_bf16 v[60:63], v[52:55], v[136:139], v[60:63]
	v_mfma_f32_16x16x32_bf16 v[60:63], v[56:59], v[144:147], v[60:63]
	v_mfma_f32_16x16x32_bf16 v[92:95], v[56:59], v[128:131], v[92:95]
	s_barrier
	v_mfma_f32_16x16x32_bf16 v[92:95], v[52:55], v[120:123], v[92:95]
	s_setprio 0
	s_add_u32 s26, s30, 0x80000
	s_addc_u32 s27, s31, 0
	s_add_i32 s58, s59, s41
	v_lshl_add_u64 v[44:45], s[26:27], 0, v[2:3]
	s_mov_b32 m0, s58
	s_nop 0
	global_load_lds_dwordx4 v[44:45], off
	v_lshl_add_u64 v[44:45], s[26:27], 0, v[172:173]
	s_add_i32 m0, s58, 0x2000
	s_nop 0
	global_load_lds_dwordx4 v[44:45], off
	s_add_i32 s58, 0, 0x18000
	v_add_u32_e32 v44, s58, v1
	ds_read_b128 v[52:55], v44
	ds_read_b128 v[56:59], v44 offset:1024
	s_waitcnt vmcnt(6)
	s_barrier
	s_setprio 1
	v_mfma_f32_16x16x32_bf16 v[40:43], v[190:193], v[136:139], v[40:43]
	v_mfma_f32_16x16x32_bf16 v[40:43], v[202:205], v[144:147], v[40:43]
	v_mfma_f32_16x16x32_bf16 v[24:27], v[202:205], v[168:171], v[24:27]
	v_mfma_f32_16x16x32_bf16 v[24:27], v[190:193], v[164:167], v[24:27]
	v_mfma_f32_16x16x32_bf16 v[8:11], v[190:193], v[182:185], v[8:11]
	v_mfma_f32_16x16x32_bf16 v[8:11], v[202:205], v[186:189], v[8:11]
	v_mfma_f32_16x16x32_bf16 v[44:47], v[202:205], v[128:131], v[88:91]
	v_mfma_f32_16x16x32_bf16 v[44:47], v[190:193], v[120:123], v[44:47]
	v_mfma_f32_16x16x32_bf16 v[48:51], v[206:209], v[120:123], v[64:67]
	v_mfma_f32_16x16x32_bf16 v[48:51], v[210:213], v[128:131], v[48:51]
	v_mfma_f32_16x16x32_bf16 v[4:7], v[210:213], v[186:189], v[4:7]
	v_mfma_f32_16x16x32_bf16 v[4:7], v[206:209], v[182:185], v[4:7]
	v_mfma_f32_16x16x32_bf16 v[20:23], v[206:209], v[164:167], v[20:23]
	v_mfma_f32_16x16x32_bf16 v[20:23], v[210:213], v[168:171], v[20:23]
	v_mfma_f32_16x16x32_bf16 v[32:35], v[210:213], v[144:147], v[32:35]
	s_barrier
	v_mfma_f32_16x16x32_bf16 v[32:35], v[206:209], v[136:139], v[32:35]
	s_setprio 0
	v_add_u32_e32 v88, s58, v1
	ds_read_b128 v[64:67], v88 offset:2048
	ds_read_b128 v[88:91], v88 offset:3072
	s_add_u32 s26, s34, 0x4000
	s_addc_u32 s27, s35, 0
	s_mov_b32 m0, s44
	v_lshl_add_u64 v[136:137], s[26:27], 0, v[176:177]
	ds_read_b128 v[120:123], v200 offset:32768
	ds_read_b128 v[128:131], v200 offset:33792
	ds_read_b128 v[164:167], v200 offset:34816
	ds_read_b128 v[168:171], v200 offset:35840
	ds_read_b128 v[182:185], v200 offset:36864
	ds_read_b128 v[186:189], v200 offset:37888
	ds_read_b128 v[190:193], v200 offset:38912
	ds_read_b128 v[202:205], v200 offset:39936
	global_load_lds_dwordx4 v[136:137], off
	v_lshl_add_u64 v[136:137], s[26:27], 0, v[174:175]
	s_mov_b32 m0, s45
	s_nop 0
	global_load_lds_dwordx4 v[136:137], off
	s_waitcnt lgkmcnt(8)
	s_barrier
	s_waitcnt lgkmcnt(0)
	s_setprio 1
	s_waitcnt lgkmcnt(0)
	v_mfma_f32_16x16x32_bf16 v[136:139], v[52:55], v[120:123], v[160:163]
	v_mfma_f32_16x16x32_bf16 v[160:163], v[56:59], v[128:131], v[136:139]
	v_mfma_f32_16x16x32_bf16 v[136:139], v[64:67], v[120:123], v[156:159]
	v_mfma_f32_16x16x32_bf16 v[156:159], v[88:91], v[128:131], v[136:139]
	v_mfma_f32_16x16x32_bf16 v[136:139], v[52:55], v[164:167], v[148:151]
	v_mfma_f32_16x16x32_bf16 v[148:151], v[56:59], v[168:171], v[136:139]
	v_mfma_f32_16x16x32_bf16 v[136:139], v[64:67], v[164:167], v[140:143]
	v_mfma_f32_16x16x32_bf16 v[140:143], v[88:91], v[168:171], v[136:139]
	v_mfma_f32_16x16x32_bf16 v[132:135], v[52:55], v[182:185], v[132:135]
	v_mfma_f32_16x16x32_bf16 v[132:135], v[56:59], v[186:189], v[132:135]
	v_mfma_f32_16x16x32_bf16 v[124:127], v[64:67], v[182:185], v[124:127]
	v_mfma_f32_16x16x32_bf16 v[124:127], v[88:91], v[186:189], v[124:127]
	v_mfma_f32_16x16x32_bf16 v[116:119], v[52:55], v[190:193], v[116:119]
	v_mfma_f32_16x16x32_bf16 v[116:119], v[56:59], v[202:205], v[116:119]
	v_mfma_f32_16x16x32_bf16 v[108:111], v[64:67], v[190:193], v[108:111]
	s_barrier
	v_mfma_f32_16x16x32_bf16 v[108:111], v[88:91], v[202:205], v[108:111]
	s_setprio 0
	s_add_i32 s34, 0, 0x1c000
	v_add_u32_e32 v136, s34, v1
	s_add_i32 s26, s58, s41
	ds_read_b128 v[206:209], v136
	ds_read_b128 v[210:213], v136 offset:1024
	ds_read_b128 v[214:217], v136 offset:2048
	ds_read_b128 v[218:221], v136 offset:3072
	v_lshl_add_u64 v[136:137], v[194:195], 0, s[2:3]
	s_mov_b32 m0, s26
	s_nop 0
	global_load_lds_dwordx4 v[136:137], off
	v_lshl_add_u64 v[136:137], v[222:223], 0, s[2:3]
	s_add_i32 m0, s26, 0x2000
	s_nop 0
	global_load_lds_dwordx4 v[136:137], off
	s_barrier
	s_waitcnt lgkmcnt(0)
	s_setprio 1
	s_waitcnt lgkmcnt(0)
	v_mfma_f32_16x16x32_bf16 v[68:71], v[214:217], v[120:123], v[68:71]
	v_mfma_f32_16x16x32_bf16 v[144:147], v[218:221], v[128:131], v[68:71]
	v_mfma_f32_16x16x32_bf16 v[136:139], v[206:209], v[120:123], v[152:155]
	v_mfma_f32_16x16x32_bf16 v[152:155], v[210:213], v[128:131], v[136:139]
	v_mfma_f32_16x16x32_bf16 v[68:71], v[206:209], v[164:167], v[72:75]
	v_mfma_f32_16x16x32_bf16 v[136:139], v[210:213], v[168:171], v[68:71]
	v_mfma_f32_16x16x32_bf16 v[68:71], v[214:217], v[164:167], v[76:79]
	v_mfma_f32_16x16x32_bf16 v[128:131], v[218:221], v[168:171], v[68:71]
	v_mfma_f32_16x16x32_bf16 v[68:71], v[206:209], v[182:185], v[80:83]
	v_mfma_f32_16x16x32_bf16 v[120:123], v[210:213], v[186:189], v[68:71]
	v_mfma_f32_16x16x32_bf16 v[68:71], v[214:217], v[182:185], v[112:115]
	v_mfma_f32_16x16x32_bf16 v[112:115], v[218:221], v[186:189], v[68:71]
	v_mfma_f32_16x16x32_bf16 v[68:71], v[206:209], v[190:193], v[104:107]
	v_mfma_f32_16x16x32_bf16 v[104:107], v[210:213], v[202:205], v[68:71]
	v_mfma_f32_16x16x32_bf16 v[68:71], v[214:217], v[190:193], v[96:99]
	s_barrier
	v_mfma_f32_16x16x32_bf16 v[96:99], v[218:221], v[202:205], v[68:71]
	s_setprio 0
	s_mov_b32 m0, s48
	v_lshl_add_u64 v[190:191], v[224:225], 0, s[2:3]
	s_nop 2
	ds_read_b128 v[68:71], v200 offset:49152
	ds_read_b128 v[72:75], v200 offset:50176
	ds_read_b128 v[76:79], v200 offset:51200
	ds_read_b128 v[80:83], v200 offset:52224
	ds_read_b128 v[164:167], v200 offset:53248
	ds_read_b128 v[168:171], v200 offset:54272
	ds_read_b128 v[182:185], v200 offset:55296
	ds_read_b128 v[186:189], v200 offset:56320
	global_load_lds_dwordx4 v[190:191], off
	v_lshl_add_u64 v[190:191], v[226:227], 0, s[2:3]
	s_mov_b32 m0, s49
	s_nop 0
	global_load_lds_dwordx4 v[190:191], off
	s_barrier
	s_waitcnt lgkmcnt(0)
	s_setprio 1
	s_waitcnt lgkmcnt(0)
	v_mfma_f32_16x16x32_bf16 v[100:103], v[52:55], v[68:71], v[100:103]
	v_mfma_f32_16x16x32_bf16 v[100:103], v[56:59], v[72:75], v[100:103]
	v_mfma_f32_16x16x32_bf16 v[84:87], v[56:59], v[80:83], v[84:87]
	v_mfma_f32_16x16x32_bf16 v[84:87], v[52:55], v[76:79], v[84:87]
	v_mfma_f32_16x16x32_bf16 v[36:39], v[52:55], v[164:167], v[36:39]
	v_mfma_f32_16x16x32_bf16 v[36:39], v[56:59], v[168:171], v[36:39]
	v_mfma_f32_16x16x32_bf16 v[16:19], v[56:59], v[186:189], v[16:19]
	v_mfma_f32_16x16x32_bf16 v[16:19], v[52:55], v[182:185], v[16:19]
	v_mfma_f32_16x16x32_bf16 v[12:15], v[64:67], v[182:185], v[12:15]
	v_mfma_f32_16x16x32_bf16 v[12:15], v[88:91], v[186:189], v[12:15]
	v_mfma_f32_16x16x32_bf16 v[28:31], v[88:91], v[168:171], v[28:31]
	v_mfma_f32_16x16x32_bf16 v[28:31], v[64:67], v[164:167], v[28:31]
	v_mfma_f32_16x16x32_bf16 v[60:63], v[64:67], v[76:79], v[60:63]
	v_mfma_f32_16x16x32_bf16 v[60:63], v[88:91], v[80:83], v[60:63]
	v_mfma_f32_16x16x32_bf16 v[92:95], v[88:91], v[72:75], v[92:95]
	s_barrier
	v_mfma_f32_16x16x32_bf16 v[92:95], v[64:67], v[68:71], v[92:95]
	s_setprio 0
	s_add_u32 s26, s30, 0x80080
	s_addc_u32 s27, s31, 0
	s_add_i32 s30, s34, s41
	s_mov_b32 m0, s30
	s_nop 0
	global_load_lds_dwordx4 v2, s[26:27]
	s_add_i32 m0, s30, 0x2000
	s_nop 0
	global_load_lds_dwordx4 v172, s[26:27]
	s_waitcnt vmcnt(6)
	s_barrier
	s_setprio 1
	v_mfma_f32_16x16x32_bf16 v[44:47], v[206:209], v[68:71], v[44:47]
	v_mfma_f32_16x16x32_bf16 v[88:91], v[210:213], v[72:75], v[44:47]
	v_mfma_f32_16x16x32_bf16 v[44:47], v[214:217], v[68:71], v[48:51]
	v_mfma_f32_16x16x32_bf16 v[64:67], v[218:221], v[72:75], v[44:47]
	v_mfma_f32_16x16x32_bf16 v[40:43], v[206:209], v[76:79], v[40:43]
	v_mfma_f32_16x16x32_bf16 v[40:43], v[210:213], v[80:83], v[40:43]
	v_mfma_f32_16x16x32_bf16 v[32:35], v[214:217], v[76:79], v[32:35]
	v_mfma_f32_16x16x32_bf16 v[32:35], v[218:221], v[80:83], v[32:35]
	v_mfma_f32_16x16x32_bf16 v[24:27], v[206:209], v[164:167], v[24:27]
	v_mfma_f32_16x16x32_bf16 v[24:27], v[210:213], v[168:171], v[24:27]
	v_mfma_f32_16x16x32_bf16 v[20:23], v[214:217], v[164:167], v[20:23]
	v_mfma_f32_16x16x32_bf16 v[20:23], v[218:221], v[168:171], v[20:23]
	v_mfma_f32_16x16x32_bf16 v[8:11], v[206:209], v[182:185], v[8:11]
	v_mfma_f32_16x16x32_bf16 v[8:11], v[210:213], v[186:189], v[8:11]
	v_mfma_f32_16x16x32_bf16 v[4:7], v[214:217], v[182:185], v[4:7]
	s_barrier
	v_mfma_f32_16x16x32_bf16 v[4:7], v[218:221], v[186:189], v[4:7]
	s_setprio 0
	s_add_i32 s57, s57, 2
	s_add_u32 s55, s55, 0x100
	s_addc_u32 s56, s56, 0
	s_cmp_gt_u32 s57, 29
	s_mov_b64 s[26:27], s[28:29]
	s_cbranch_scc0 .LBB0_1002
	v_lshl_or_b32 v182, s52, 7, v197
	v_ashrrev_i32_e32 v183, 31, v182
	v_lshlrev_b64 v[56:57], 2, v[182:183]
	v_lshl_add_u64 v[48:49], s[10:11], 0, v[56:57]
	global_load_dwordx4 v[44:47], v[48:49], off offset:16
	global_load_dwordx4 v[68:71], v[48:49], off
	v_lshl_add_u64 v[52:53], s[14:15], 0, v[56:57]
	global_load_dwordx4 v[48:51], v[52:53], off offset:16
	global_load_dwordx4 v[72:75], v[52:53], off
	v_lshl_add_u64 v[58:59], s[16:17], 0, v[56:57]
	global_load_dwordx4 v[52:55], v[58:59], off offset:16
	global_load_dwordx4 v[76:79], v[58:59], off
	v_lshl_add_u64 v[80:81], s[12:13], 0, v[56:57]
	global_load_dwordx4 v[56:59], v[80:81], off offset:16
	s_nop 0
	global_load_dwordx4 v[80:83], v[80:81], off
	v_mov_b32_dpp v164, v8 row_shr:1 row_mask:0xf bank_mask:0xf bound_ctrl:1
	v_mov_b32_dpp v165, v9 row_shr:1 row_mask:0xf bank_mask:0xf bound_ctrl:1
	v_mov_b32_dpp v166, v10 row_shr:1 row_mask:0xf bank_mask:0xf bound_ctrl:1
	v_mov_b32_dpp v167, v11 row_shr:1 row_mask:0xf bank_mask:0xf bound_ctrl:1
	v_mov_b32_dpp v168, v4 row_shr:1 row_mask:0xf bank_mask:0xf bound_ctrl:1
	v_mov_b32_dpp v169, v5 row_shr:1 row_mask:0xf bank_mask:0xf bound_ctrl:1
	v_mov_b32_dpp v170, v6 row_shr:1 row_mask:0xf bank_mask:0xf bound_ctrl:1
	v_mov_b32_dpp v171, v7 row_shr:1 row_mask:0xf bank_mask:0xf bound_ctrl:1
	v_lshl_add_u32 v201, s33, 8, v196
	s_movk_i32 s21, 0x2c00
	s_lshl_b32 s19, s33, 2
	v_mov_b32_dpp v190, v152 row_shl:1 row_mask:0xf bank_mask:0xf bound_ctrl:1
	v_mov_b32_dpp v191, v153 row_shl:1 row_mask:0xf bank_mask:0xf bound_ctrl:1
	v_mov_b32_dpp v188, v154 row_shl:1 row_mask:0xf bank_mask:0xf bound_ctrl:1
	v_mov_b32_dpp v189, v155 row_shl:1 row_mask:0xf bank_mask:0xf bound_ctrl:1
	v_mov_b32_dpp v186, v144 row_shl:1 row_mask:0xf bank_mask:0xf bound_ctrl:1
	v_mov_b32_dpp v187, v145 row_shl:1 row_mask:0xf bank_mask:0xf bound_ctrl:1
	v_mov_b32_dpp v184, v146 row_shl:1 row_mask:0xf bank_mask:0xf bound_ctrl:1
	v_mov_b32_dpp v185, v147 row_shl:1 row_mask:0xf bank_mask:0xf bound_ctrl:1
	s_add_i32 s19, s19, s50
	s_waitcnt vmcnt(0)
	v_pk_mul_f32 v[168:169], v[44:45], v[168:169]
	v_pk_mul_f32 v[164:165], v[68:69], v[164:165]
	v_pk_mul_f32 v[166:167], v[70:71], v[166:167]
	v_pk_fma_f32 v[164:165], v[152:153], v[72:73], v[164:165]
	v_pk_fma_f32 v[166:167], v[154:155], v[74:75], v[166:167]
	v_pk_fma_f32 v[164:165], v[136:137], v[76:77], v[164:165]
	v_pk_fma_f32 v[166:167], v[138:139], v[78:79], v[166:167]
	v_pk_add_f32 v[164:165], v[80:81], v[164:165]
	v_pk_add_f32 v[166:167], v[82:83], v[166:167]
	v_mul_f32_e32 v192, 0xbfb8aa3b, v164
	v_mul_f32_e32 v193, 0xbfb8aa3b, v165
	v_exp_f32_e32 v192, v192
	v_exp_f32_e32 v193, v193
	v_pk_fma_f32 v[168:169], v[144:145], v[48:49], v[168:169]
	v_pk_mul_f32 v[170:171], v[46:47], v[170:171]
	v_pk_fma_f32 v[168:169], v[128:129], v[52:53], v[168:169]
	v_pk_add_f32 v[192:193], v[192:193], 1.0 op_sel_hi:[1,0]
	v_pk_add_f32 v[168:169], v[56:57], v[168:169]
	v_div_scale_f32 v194, s[26:27], v193, v193, 1.0
	v_rcp_f32_e32 v195, v194
	v_pk_fma_f32 v[170:171], v[146:147], v[50:51], v[170:171]
	v_fma_f32 v202, -v194, v195, 1.0
	v_fmac_f32_e32 v195, v202, v195
	v_div_scale_f32 v202, vcc, 1.0, v193, 1.0
	v_mul_f32_e32 v203, v202, v195
	v_fma_f32 v204, -v194, v203, v202
	v_fmac_f32_e32 v203, v204, v195
	v_fma_f32 v194, -v194, v203, v202
	v_div_fmas_f32 v194, v194, v195, v203
	v_div_fixup_f32 v193, v194, v193, 1.0
	v_div_scale_f32 v194, s[26:27], v192, v192, 1.0
	v_rcp_f32_e32 v195, v194
	v_pk_fma_f32 v[170:171], v[130:131], v[54:55], v[170:171]
	v_fma_f32 v202, -v194, v195, 1.0
	v_fmac_f32_e32 v195, v202, v195
	v_div_scale_f32 v202, vcc, 1.0, v192, 1.0
	v_mul_f32_e32 v203, v202, v195
	v_fma_f32 v204, -v194, v203, v202
	v_fmac_f32_e32 v203, v204, v195
	v_fma_f32 v194, -v194, v203, v202
	v_div_fmas_f32 v194, v194, v195, v203
	v_div_fixup_f32 v192, v194, v192, 1.0
	v_mul_f32_e32 v194, 0xbfb8aa3b, v166
	v_mul_f32_e32 v195, 0xbfb8aa3b, v167
	v_exp_f32_e32 v194, v194
	v_exp_f32_e32 v195, v195
	v_pk_add_f32 v[170:171], v[58:59], v[170:171]
	v_pk_mul_f32 v[192:193], v[164:165], v[192:193]
	v_pk_add_f32 v[194:195], v[194:195], 1.0 op_sel_hi:[1,0]
	s_nop 0
	v_div_scale_f32 v202, s[26:27], v195, v195, 1.0
	v_rcp_f32_e32 v203, v202
	v_pk_mul_f32 v[192:193], v[160:161], v[192:193]
	v_fma_f32 v204, -v202, v203, 1.0
	v_fmac_f32_e32 v203, v204, v203
	v_div_scale_f32 v204, vcc, 1.0, v195, 1.0
	v_mul_f32_e32 v205, v204, v203
	v_fma_f32 v206, -v202, v205, v204
	v_fmac_f32_e32 v205, v206, v203
	v_fma_f32 v202, -v202, v205, v204
	v_div_fmas_f32 v202, v202, v203, v205
	v_div_fixup_f32 v195, v202, v195, 1.0
	v_div_scale_f32 v202, s[26:27], v194, v194, 1.0
	v_rcp_f32_e32 v203, v202
	v_cvt_pk_bf16_f32 v192, v192, v193
	v_fma_f32 v204, -v202, v203, 1.0
	v_fmac_f32_e32 v203, v204, v203
	v_div_scale_f32 v204, vcc, 1.0, v194, 1.0
	v_mul_f32_e32 v205, v204, v203
	v_fma_f32 v206, -v202, v205, v204
	v_fmac_f32_e32 v205, v206, v203
	v_fma_f32 v202, -v202, v205, v204
	v_div_fmas_f32 v202, v202, v203, v205
	v_div_fixup_f32 v194, v202, v194, 1.0
	v_mul_f32_e32 v202, 0xbfb8aa3b, v168
	v_mul_f32_e32 v203, 0xbfb8aa3b, v169
	v_exp_f32_e32 v202, v202
	v_exp_f32_e32 v203, v203
	v_pk_mul_f32 v[194:195], v[166:167], v[194:195]
	v_pk_add_f32 v[202:203], v[202:203], 1.0 op_sel_hi:[1,0]
	s_nop 0
	v_div_scale_f32 v204, s[26:27], v203, v203, 1.0
	v_rcp_f32_e32 v205, v204
	v_pk_mul_f32 v[194:195], v[162:163], v[194:195]
	v_fma_f32 v206, -v204, v205, 1.0
	v_fmac_f32_e32 v205, v206, v205
	v_div_scale_f32 v206, vcc, 1.0, v203, 1.0
	v_mul_f32_e32 v207, v206, v205
	v_fma_f32 v208, -v204, v207, v206
	v_fmac_f32_e32 v207, v208, v205
	v_fma_f32 v204, -v204, v207, v206
	v_div_fmas_f32 v204, v204, v205, v207
	v_div_fixup_f32 v203, v204, v203, 1.0
	v_div_scale_f32 v204, s[26:27], v202, v202, 1.0
	v_rcp_f32_e32 v205, v204
	v_cvt_pk_bf16_f32 v193, v194, v195
	v_fma_f32 v206, -v204, v205, 1.0
	v_fmac_f32_e32 v205, v206, v205
	v_div_scale_f32 v206, vcc, 1.0, v202, 1.0
	v_mul_f32_e32 v207, v206, v205
	v_fma_f32 v208, -v204, v207, v206
	v_fmac_f32_e32 v207, v208, v205
	v_fma_f32 v204, -v204, v207, v206
	v_div_fmas_f32 v204, v204, v205, v207
	v_div_fixup_f32 v202, v204, v202, 1.0
	v_mul_f32_e32 v204, 0xbfb8aa3b, v170
	v_mul_f32_e32 v205, 0xbfb8aa3b, v171
	v_exp_f32_e32 v204, v204
	v_exp_f32_e32 v205, v205
	v_pk_mul_f32 v[202:203], v[168:169], v[202:203]
	v_pk_add_f32 v[204:205], v[204:205], 1.0 op_sel_hi:[1,0]
	s_nop 0
	v_div_scale_f32 v206, s[26:27], v205, v205, 1.0
	v_rcp_f32_e32 v207, v206
	v_pk_mul_f32 v[202:203], v[156:157], v[202:203]
	v_fma_f32 v208, -v206, v207, 1.0
	v_fmac_f32_e32 v207, v208, v207
	v_div_scale_f32 v208, vcc, 1.0, v205, 1.0
	v_mul_f32_e32 v209, v208, v207
	v_fma_f32 v210, -v206, v209, v208
	v_fmac_f32_e32 v209, v210, v207
	v_fma_f32 v206, -v206, v209, v208
	v_div_fmas_f32 v206, v206, v207, v209
	v_div_fixup_f32 v205, v206, v205, 1.0
	v_div_scale_f32 v206, s[26:27], v204, v204, 1.0
	v_rcp_f32_e32 v207, v206
	v_cvt_pk_bf16_f32 v194, v202, v203
	v_mov_b64_e32 v[202:203], s[0:1]
	v_mad_i64_i32 v[202:203], s[26:27], v201, s21, v[202:203]
	v_fma_f32 v208, -v206, v207, 1.0
	v_fmac_f32_e32 v207, v208, v207
	v_div_scale_f32 v208, vcc, 1.0, v204, 1.0
	v_mul_f32_e32 v209, v208, v207
	v_fma_f32 v210, -v206, v209, v208
	v_fmac_f32_e32 v209, v210, v207
	v_fma_f32 v206, -v206, v209, v208
	v_div_fmas_f32 v206, v206, v207, v209
	v_div_fixup_f32 v204, v206, v204, 1.0
	v_pk_mul_f32 v[204:205], v[170:171], v[204:205]
	v_lshl_add_u64 v[202:203], v[182:183], 1, v[202:203]
	v_pk_mul_f32 v[204:205], v[158:159], v[204:205]
	s_nop 0
	v_cvt_pk_bf16_f32 v195, v204, v205
	global_store_dwordx4 v[202:203], v[192:195], off
	s_and_saveexec_b64 s[26:27], s[6:7]
	s_cbranch_execz .LBB0_1005
	s_mul_i32 s28, s19, 0x10800
	s_mul_hi_i32 s21, s19, 0x10800
	s_add_u32 s28, s46, s28
	s_addc_u32 s29, s47, s21
	v_lshl_add_u64 v[192:193], v[182:183], 2, s[28:29]
	global_store_dwordx4 v[192:193], v[164:167], off
	global_store_dwordx4 v[192:193], v[168:171], off offset:16
	s_nop 0
	v_add_co_u32_e32 v164, vcc, 0x5000, v192
	s_nop 1
	v_addc_co_u32_e32 v165, vcc, 0, v193, vcc
	global_store_dwordx4 v[164:165], v[160:163], off offset:2048
	global_store_dwordx4 v[164:165], v[156:159], off offset:2064
	s_nop 1
	v_add_co_u32_e32 v156, vcc, 0xb000, v192
	s_nop 1
	v_addc_co_u32_e32 v157, vcc, 0, v193, vcc
	global_store_dwordx4 v[156:157], v[152:155], off
	global_store_dwordx4 v[156:157], v[144:147], off offset:16

.LBB0_1180:
	s_add_u32 s16, s14, 0x100
	s_addc_u32 s17, s15, 0
	s_add_i32 s45, 0, 0x10000
	v_add_u32_e32 v144, s45, v200
	ds_read_b128 v[132:135], v144
	ds_read_b128 v[136:139], v144 offset:1024
	ds_read_b128 v[140:143], v144 offset:2048
	ds_read_b128 v[144:147], v144 offset:3072
	s_cmpk_eq_i32 s44, 0x54
	s_cselect_b32 s21, s1, s17
	s_cselect_b32 s20, s0, s16
	s_cselect_b32 s19, s7, s43
	s_cselect_b32 s18, s6, s42
	s_add_i32 m0, s28, 0xc000
	ds_read_b128 v[148:151], v202
	ds_read_b128 v[152:155], v202 offset:1024
	ds_read_b128 v[156:159], v202 offset:2048
	ds_read_b128 v[160:163], v202 offset:3072
	ds_read_b128 v[164:167], v202 offset:4096
	ds_read_b128 v[168:171], v202 offset:5120
	ds_read_b128 v[172:175], v202 offset:6144
	ds_read_b128 v[186:189], v202 offset:7168
	global_load_lds_dwordx4 v182, s[14:15]
	s_add_i32 m0, s28, 0xe000
	s_nop 0
	global_load_lds_dwordx4 v184, s[14:15]
	s_waitcnt lgkmcnt(8)
	s_barrier
	s_waitcnt lgkmcnt(0)
	s_setprio 1
	s_waitcnt lgkmcnt(0)
	v_mfma_f32_16x16x32_bf16 v[128:131], v[132:135], v[148:151], v[128:131]
	v_mfma_f32_16x16x32_bf16 v[128:131], v[136:139], v[152:155], v[128:131]
	v_mfma_f32_16x16x32_bf16 v[112:115], v[136:139], v[160:163], v[112:115]
	v_mfma_f32_16x16x32_bf16 v[112:115], v[132:135], v[156:159], v[112:115]
	v_mfma_f32_16x16x32_bf16 v[96:99], v[132:135], v[164:167], v[96:99]
	v_mfma_f32_16x16x32_bf16 v[96:99], v[136:139], v[168:171], v[96:99]
	v_mfma_f32_16x16x32_bf16 v[80:83], v[136:139], v[186:189], v[80:83]
	v_mfma_f32_16x16x32_bf16 v[80:83], v[132:135], v[172:175], v[80:83]
	v_mfma_f32_16x16x32_bf16 v[76:79], v[140:143], v[172:175], v[76:79]
	v_mfma_f32_16x16x32_bf16 v[76:79], v[144:147], v[186:189], v[76:79]
	v_mfma_f32_16x16x32_bf16 v[92:95], v[144:147], v[168:171], v[92:95]
	v_mfma_f32_16x16x32_bf16 v[92:95], v[140:143], v[164:167], v[92:95]
	v_mfma_f32_16x16x32_bf16 v[108:111], v[140:143], v[156:159], v[108:111]
	v_mfma_f32_16x16x32_bf16 v[108:111], v[144:147], v[160:163], v[108:111]
	v_mfma_f32_16x16x32_bf16 v[124:127], v[144:147], v[152:155], v[124:127]
	s_barrier
	v_mfma_f32_16x16x32_bf16 v[124:127], v[140:143], v[148:151], v[124:127]
	s_setprio 0
	s_add_i32 s46, 0, 0x14000
	s_add_i32 s14, s45, s27
	v_add_u32_e32 v203, s46, v200
	v_lshl_add_u64 v[212:213], s[18:19], 0, v[2:3]
	s_mov_b32 m0, s14
	ds_read_b128 v[190:193], v203
	ds_read_b128 v[194:197], v203 offset:1024
	ds_read_b128 v[204:207], v203 offset:2048
	ds_read_b128 v[208:211], v203 offset:3072
	global_load_lds_dwordx4 v[212:213], off
	v_lshl_add_u64 v[214:215], s[18:19], 0, v[176:177]
	s_add_i32 m0, s14, 0x2000
	s_nop 0
	global_load_lds_dwordx4 v[214:215], off
	s_barrier
	s_waitcnt lgkmcnt(0)
	s_setprio 1
	s_waitcnt lgkmcnt(0)
	v_mfma_f32_16x16x32_bf16 v[120:123], v[190:193], v[148:151], v[120:123]
	v_mfma_f32_16x16x32_bf16 v[120:123], v[194:197], v[152:155], v[120:123]
	v_mfma_f32_16x16x32_bf16 v[104:107], v[194:197], v[160:163], v[104:107]
	v_mfma_f32_16x16x32_bf16 v[104:107], v[190:193], v[156:159], v[104:107]
	v_mfma_f32_16x16x32_bf16 v[88:91], v[190:193], v[164:167], v[88:91]
	v_mfma_f32_16x16x32_bf16 v[88:91], v[194:197], v[168:171], v[88:91]
	v_mfma_f32_16x16x32_bf16 v[72:75], v[194:197], v[186:189], v[72:75]
	v_mfma_f32_16x16x32_bf16 v[72:75], v[190:193], v[172:175], v[72:75]
	v_mfma_f32_16x16x32_bf16 v[68:71], v[204:207], v[172:175], v[68:71]
	v_mfma_f32_16x16x32_bf16 v[68:71], v[208:211], v[186:189], v[68:71]
	v_mfma_f32_16x16x32_bf16 v[84:87], v[208:211], v[168:171], v[84:87]
	v_mfma_f32_16x16x32_bf16 v[84:87], v[204:207], v[164:167], v[84:87]
	v_mfma_f32_16x16x32_bf16 v[100:103], v[204:207], v[156:159], v[100:103]
	v_mfma_f32_16x16x32_bf16 v[100:103], v[208:211], v[160:163], v[100:103]
	v_mfma_f32_16x16x32_bf16 v[116:119], v[208:211], v[152:155], v[116:119]
	s_barrier
	v_mfma_f32_16x16x32_bf16 v[116:119], v[204:207], v[148:151], v[116:119]
	s_setprio 0
	s_mov_b32 m0, s28
	v_lshl_add_u64 v[216:217], s[20:21], 0, v[180:181]
	ds_read_b128 v[148:151], v202 offset:16384
	ds_read_b128 v[152:155], v202 offset:17408
	ds_read_b128 v[156:159], v202 offset:18432
	ds_read_b128 v[160:163], v202 offset:19456
	ds_read_b128 v[164:167], v202 offset:20480
	ds_read_b128 v[168:171], v202 offset:21504
	ds_read_b128 v[172:175], v202 offset:22528
	ds_read_b128 v[186:189], v202 offset:23552
	global_load_lds_dwordx4 v[216:217], off
	v_lshl_add_u64 v[218:219], s[20:21], 0, v[178:179]
	s_mov_b32 m0, s29
	s_nop 0
	global_load_lds_dwordx4 v[218:219], off
	s_waitcnt vmcnt(10)
	s_barrier
	s_waitcnt lgkmcnt(0)
	s_setprio 1
	s_waitcnt lgkmcnt(0)
	v_mfma_f32_16x16x32_bf16 v[64:67], v[132:135], v[148:151], v[64:67]
	v_mfma_f32_16x16x32_bf16 v[64:67], v[136:139], v[152:155], v[64:67]
	v_mfma_f32_16x16x32_bf16 v[48:51], v[136:139], v[160:163], v[48:51]
	v_mfma_f32_16x16x32_bf16 v[48:51], v[132:135], v[156:159], v[48:51]
	v_mfma_f32_16x16x32_bf16 v[32:35], v[132:135], v[164:167], v[32:35]
	v_mfma_f32_16x16x32_bf16 v[32:35], v[136:139], v[168:171], v[32:35]
	v_mfma_f32_16x16x32_bf16 v[16:19], v[136:139], v[186:189], v[16:19]
	v_mfma_f32_16x16x32_bf16 v[16:19], v[132:135], v[172:175], v[16:19]
	v_mfma_f32_16x16x32_bf16 v[12:15], v[140:143], v[172:175], v[12:15]
	v_mfma_f32_16x16x32_bf16 v[12:15], v[144:147], v[186:189], v[12:15]
	v_mfma_f32_16x16x32_bf16 v[28:31], v[144:147], v[168:171], v[28:31]
	v_mfma_f32_16x16x32_bf16 v[28:31], v[140:143], v[164:167], v[28:31]
	v_mfma_f32_16x16x32_bf16 v[44:47], v[140:143], v[156:159], v[44:47]
	v_mfma_f32_16x16x32_bf16 v[44:47], v[144:147], v[160:163], v[44:47]
	v_mfma_f32_16x16x32_bf16 v[60:63], v[144:147], v[152:155], v[60:63]
	s_barrier
	v_mfma_f32_16x16x32_bf16 v[60:63], v[140:143], v[148:151], v[60:63]
	s_setprio 0
	s_add_u32 s14, s18, 0x160000
	s_addc_u32 s15, s19, 0
	s_add_i32 s45, s46, s27
	v_lshl_add_u64 v[132:133], s[14:15], 0, v[2:3]
	s_mov_b32 m0, s45
	s_nop 0
	global_load_lds_dwordx4 v[132:133], off
	v_lshl_add_u64 v[132:133], s[14:15], 0, v[176:177]
	s_add_i32 m0, s45, 0x2000
	s_nop 0
	global_load_lds_dwordx4 v[132:133], off
	s_add_i32 s45, 0, 0x18000
	v_add_u32_e32 v144, s45, v200
	ds_read_b128 v[132:135], v144
	ds_read_b128 v[136:139], v144 offset:1024
	ds_read_b128 v[140:143], v144 offset:2048
	ds_read_b128 v[144:147], v144 offset:3072
	s_waitcnt vmcnt(6)
	s_barrier
	s_setprio 1
	v_mfma_f32_16x16x32_bf16 v[56:59], v[190:193], v[148:151], v[56:59]
	v_mfma_f32_16x16x32_bf16 v[56:59], v[194:197], v[152:155], v[56:59]
	v_mfma_f32_16x16x32_bf16 v[40:43], v[194:197], v[160:163], v[40:43]
	v_mfma_f32_16x16x32_bf16 v[40:43], v[190:193], v[156:159], v[40:43]
	v_mfma_f32_16x16x32_bf16 v[24:27], v[190:193], v[164:167], v[24:27]
	v_mfma_f32_16x16x32_bf16 v[24:27], v[194:197], v[168:171], v[24:27]
	v_mfma_f32_16x16x32_bf16 v[8:11], v[194:197], v[186:189], v[8:11]
	v_mfma_f32_16x16x32_bf16 v[8:11], v[190:193], v[172:175], v[8:11]
	v_mfma_f32_16x16x32_bf16 v[4:7], v[204:207], v[172:175], v[4:7]
	v_mfma_f32_16x16x32_bf16 v[4:7], v[208:211], v[186:189], v[4:7]
	v_mfma_f32_16x16x32_bf16 v[20:23], v[208:211], v[168:171], v[20:23]
	v_mfma_f32_16x16x32_bf16 v[20:23], v[204:207], v[164:167], v[20:23]
	v_mfma_f32_16x16x32_bf16 v[36:39], v[204:207], v[156:159], v[36:39]
	v_mfma_f32_16x16x32_bf16 v[36:39], v[208:211], v[160:163], v[36:39]
	v_mfma_f32_16x16x32_bf16 v[52:55], v[208:211], v[152:155], v[52:55]
	s_barrier
	v_mfma_f32_16x16x32_bf16 v[52:55], v[204:207], v[148:151], v[52:55]
	s_setprio 0
	s_add_u32 s14, s20, 0x160000
	s_addc_u32 s15, s21, 0
	s_mov_b32 m0, s30
	ds_read_b128 v[148:151], v202 offset:32768
	ds_read_b128 v[152:155], v202 offset:33792
	ds_read_b128 v[156:159], v202 offset:34816
	ds_read_b128 v[160:163], v202 offset:35840
	ds_read_b128 v[164:167], v202 offset:36864
	ds_read_b128 v[168:171], v202 offset:37888
	ds_read_b128 v[172:175], v202 offset:38912
	ds_read_b128 v[186:189], v202 offset:39936
	global_load_lds_dwordx4 v180, s[14:15]
	s_mov_b32 m0, s31
	s_nop 0
	global_load_lds_dwordx4 v178, s[14:15]
	s_waitcnt lgkmcnt(8)
	s_barrier
	s_waitcnt lgkmcnt(0)
	s_setprio 1
	s_waitcnt lgkmcnt(0)
	v_mfma_f32_16x16x32_bf16 v[128:131], v[132:135], v[148:151], v[128:131]
	v_mfma_f32_16x16x32_bf16 v[128:131], v[136:139], v[152:155], v[128:131]
	v_mfma_f32_16x16x32_bf16 v[112:115], v[136:139], v[160:163], v[112:115]
	v_mfma_f32_16x16x32_bf16 v[112:115], v[132:135], v[156:159], v[112:115]
	v_mfma_f32_16x16x32_bf16 v[96:99], v[132:135], v[164:167], v[96:99]
	v_mfma_f32_16x16x32_bf16 v[96:99], v[136:139], v[168:171], v[96:99]
	v_mfma_f32_16x16x32_bf16 v[80:83], v[136:139], v[186:189], v[80:83]
	v_mfma_f32_16x16x32_bf16 v[80:83], v[132:135], v[172:175], v[80:83]
	v_mfma_f32_16x16x32_bf16 v[76:79], v[140:143], v[172:175], v[76:79]
	v_mfma_f32_16x16x32_bf16 v[76:79], v[144:147], v[186:189], v[76:79]
	v_mfma_f32_16x16x32_bf16 v[92:95], v[144:147], v[168:171], v[92:95]
	v_mfma_f32_16x16x32_bf16 v[92:95], v[140:143], v[164:167], v[92:95]
	v_mfma_f32_16x16x32_bf16 v[108:111], v[140:143], v[156:159], v[108:111]
	v_mfma_f32_16x16x32_bf16 v[108:111], v[144:147], v[160:163], v[108:111]
	v_mfma_f32_16x16x32_bf16 v[124:127], v[144:147], v[152:155], v[124:127]
	s_barrier
	v_mfma_f32_16x16x32_bf16 v[124:127], v[140:143], v[148:151], v[124:127]
	s_setprio 0
	s_add_i32 s20, 0, 0x1c000
	s_add_i32 s14, s45, s27
	v_add_u32_e32 v203, s20, v200
	v_lshl_add_u64 v[212:213], v[212:213], 0, s[2:3]
	s_mov_b32 m0, s14
	ds_read_b128 v[190:193], v203
	ds_read_b128 v[194:197], v203 offset:1024
	ds_read_b128 v[204:207], v203 offset:2048
	ds_read_b128 v[208:211], v203 offset:3072
	global_load_lds_dwordx4 v[212:213], off
	v_lshl_add_u64 v[212:213], v[214:215], 0, s[2:3]
	s_add_i32 m0, s14, 0x2000
	s_nop 0
	global_load_lds_dwordx4 v[212:213], off
	s_barrier
	s_waitcnt lgkmcnt(0)
	s_setprio 1
	s_waitcnt lgkmcnt(0)
	v_mfma_f32_16x16x32_bf16 v[120:123], v[190:193], v[148:151], v[120:123]
	v_mfma_f32_16x16x32_bf16 v[120:123], v[194:197], v[152:155], v[120:123]
	v_mfma_f32_16x16x32_bf16 v[104:107], v[194:197], v[160:163], v[104:107]
	v_mfma_f32_16x16x32_bf16 v[104:107], v[190:193], v[156:159], v[104:107]
	v_mfma_f32_16x16x32_bf16 v[88:91], v[190:193], v[164:167], v[88:91]
	v_mfma_f32_16x16x32_bf16 v[88:91], v[194:197], v[168:171], v[88:91]
	v_mfma_f32_16x16x32_bf16 v[72:75], v[194:197], v[186:189], v[72:75]
	v_mfma_f32_16x16x32_bf16 v[72:75], v[190:193], v[172:175], v[72:75]
	v_mfma_f32_16x16x32_bf16 v[68:71], v[204:207], v[172:175], v[68:71]
	v_mfma_f32_16x16x32_bf16 v[68:71], v[208:211], v[186:189], v[68:71]
	v_mfma_f32_16x16x32_bf16 v[84:87], v[208:211], v[168:171], v[84:87]
	v_mfma_f32_16x16x32_bf16 v[84:87], v[204:207], v[164:167], v[84:87]
	v_mfma_f32_16x16x32_bf16 v[100:103], v[204:207], v[156:159], v[100:103]
	v_mfma_f32_16x16x32_bf16 v[100:103], v[208:211], v[160:163], v[100:103]
	v_mfma_f32_16x16x32_bf16 v[116:119], v[208:211], v[152:155], v[116:119]
	s_barrier
	v_mfma_f32_16x16x32_bf16 v[116:119], v[204:207], v[148:151], v[116:119]
	s_setprio 0
	s_mov_b32 m0, s36
	v_lshl_add_u64 v[212:213], v[216:217], 0, s[2:3]
	ds_read_b128 v[148:151], v202 offset:49152
	ds_read_b128 v[152:155], v202 offset:50176
	ds_read_b128 v[156:159], v202 offset:51200
	ds_read_b128 v[160:163], v202 offset:52224
	ds_read_b128 v[164:167], v202 offset:53248
	ds_read_b128 v[168:171], v202 offset:54272
	ds_read_b128 v[172:175], v202 offset:55296
	ds_read_b128 v[186:189], v202 offset:56320
	global_load_lds_dwordx4 v[212:213], off
	v_lshl_add_u64 v[212:213], v[218:219], 0, s[2:3]
	s_mov_b32 m0, s37
	s_nop 0
	global_load_lds_dwordx4 v[212:213], off
	s_barrier
	s_waitcnt lgkmcnt(0)
	s_setprio 1
	s_waitcnt lgkmcnt(0)
	v_mfma_f32_16x16x32_bf16 v[64:67], v[132:135], v[148:151], v[64:67]
	v_mfma_f32_16x16x32_bf16 v[64:67], v[136:139], v[152:155], v[64:67]
	v_mfma_f32_16x16x32_bf16 v[48:51], v[136:139], v[160:163], v[48:51]
	v_mfma_f32_16x16x32_bf16 v[48:51], v[132:135], v[156:159], v[48:51]
	v_mfma_f32_16x16x32_bf16 v[32:35], v[132:135], v[164:167], v[32:35]
	v_mfma_f32_16x16x32_bf16 v[32:35], v[136:139], v[168:171], v[32:35]
	v_mfma_f32_16x16x32_bf16 v[16:19], v[136:139], v[186:189], v[16:19]
	v_mfma_f32_16x16x32_bf16 v[16:19], v[132:135], v[172:175], v[16:19]
	v_mfma_f32_16x16x32_bf16 v[12:15], v[140:143], v[172:175], v[12:15]
	v_mfma_f32_16x16x32_bf16 v[12:15], v[144:147], v[186:189], v[12:15]
	v_mfma_f32_16x16x32_bf16 v[28:31], v[144:147], v[168:171], v[28:31]
	v_mfma_f32_16x16x32_bf16 v[28:31], v[140:143], v[164:167], v[28:31]
	v_mfma_f32_16x16x32_bf16 v[44:47], v[140:143], v[156:159], v[44:47]
	v_mfma_f32_16x16x32_bf16 v[44:47], v[144:147], v[160:163], v[44:47]
	v_mfma_f32_16x16x32_bf16 v[60:63], v[144:147], v[152:155], v[60:63]
	s_barrier
	v_mfma_f32_16x16x32_bf16 v[60:63], v[140:143], v[148:151], v[60:63]
	s_setprio 0
	s_add_u32 s14, s18, 0x160080
	s_addc_u32 s15, s19, 0
	s_add_i32 s18, s20, s27
	v_lshl_add_u64 v[132:133], s[14:15], 0, v[2:3]
	s_mov_b32 m0, s18
	s_nop 0
	global_load_lds_dwordx4 v[132:133], off
	v_lshl_add_u64 v[132:133], s[14:15], 0, v[176:177]
	s_add_i32 m0, s18, 0x2000
	s_nop 0
	global_load_lds_dwordx4 v[132:133], off
	s_waitcnt vmcnt(6)
	s_barrier
	s_setprio 1
	v_mfma_f32_16x16x32_bf16 v[56:59], v[190:193], v[148:151], v[56:59]
	v_mfma_f32_16x16x32_bf16 v[56:59], v[194:197], v[152:155], v[56:59]
	v_mfma_f32_16x16x32_bf16 v[40:43], v[194:197], v[160:163], v[40:43]
	v_mfma_f32_16x16x32_bf16 v[40:43], v[190:193], v[156:159], v[40:43]
	v_mfma_f32_16x16x32_bf16 v[24:27], v[190:193], v[164:167], v[24:27]
	v_mfma_f32_16x16x32_bf16 v[24:27], v[194:197], v[168:171], v[24:27]
	v_mfma_f32_16x16x32_bf16 v[8:11], v[194:197], v[186:189], v[8:11]
	v_mfma_f32_16x16x32_bf16 v[8:11], v[190:193], v[172:175], v[8:11]
	v_mfma_f32_16x16x32_bf16 v[4:7], v[204:207], v[172:175], v[4:7]
	v_mfma_f32_16x16x32_bf16 v[4:7], v[208:211], v[186:189], v[4:7]
	v_mfma_f32_16x16x32_bf16 v[20:23], v[208:211], v[168:171], v[20:23]
	v_mfma_f32_16x16x32_bf16 v[20:23], v[204:207], v[164:167], v[20:23]
	v_mfma_f32_16x16x32_bf16 v[36:39], v[204:207], v[156:159], v[36:39]
	v_mfma_f32_16x16x32_bf16 v[36:39], v[208:211], v[160:163], v[36:39]
	v_mfma_f32_16x16x32_bf16 v[52:55], v[208:211], v[152:155], v[52:55]
	s_barrier
	v_mfma_f32_16x16x32_bf16 v[52:55], v[204:207], v[148:151], v[52:55]
	s_setprio 0
	s_add_i32 s44, s44, 2
	s_add_u32 s42, s42, 0x100
	s_addc_u32 s43, s43, 0
	s_cmpk_gt_u32 s44, 0x55
	s_mov_b64 s[14:15], s[16:17]
	s_cbranch_scc0 .LBB0_1180
	s_cmp_lt_i32 s41, 32
	s_mov_b64 s[14:15], 0
	s_cbranch_scc1 .LBB0_1183
	s_sub_i32 s14, s41, 32
	s_lshr_b32 s14, s14, 4
	s_add_i32 s14, s14, 1
	s_mul_hi_u32 s15, s14, 0x3000
	s_mulk_i32 s14, 0x3000
